# accsnake MFMA order + no GEMM setprio + static s_setprio 1 for waves 0-3 during P7
# speedup vs baseline: 1.0180x; 1.0006x over previous
.LBB0_101:
	ds_read_b128 v[154:157], v151
	ds_read_b128 v[158:161], v151 offset:1024
	ds_read_b128 v[162:165], v151 offset:2048
	ds_read_b128 v[166:169], v151 offset:3072
	ds_read_b128 v[170:173], v152
	ds_read_b128 v[174:177], v152 offset:1024
	ds_read_b128 v[188:191], v152 offset:2048
	ds_read_b128 v[192:195], v152 offset:3072
	s_add_u32 s40, s36, s38
	s_addc_u32 s41, s37, s39
	s_add_u32 s44, s40, 0x100
	s_addc_u32 s45, s41, 0
	s_add_u32 s42, s66, s38
	s_addc_u32 s43, s67, s39
	s_add_u32 s40, s40, 0x180
	s_addc_u32 s41, s41, 0
	s_cmpk_eq_i32 s38, 0x1f00
	s_cselect_b32 s41, s65, s41
	s_cselect_b32 s40, s64, s40
	s_cselect_b32 s43, s35, s43
	s_cselect_b32 s42, s34, s42
	s_cselect_b32 s45, s23, s45
	s_cselect_b32 s44, s22, s44
	s_mov_b32 m0, s57
	v_lshl_add_u64 v[178:179], v[146:147], 0, s[38:39]
	ds_read_b128 v[196:199], v153
	ds_read_b128 v[200:203], v153 offset:1024
	ds_read_b128 v[204:207], v153 offset:2048
	ds_read_b128 v[208:211], v153 offset:3072
	ds_read_b128 v[214:217], v153 offset:4096
	ds_read_b128 v[218:221], v153 offset:5120
	ds_read_b128 v[222:225], v153 offset:6144
	ds_read_b128 v[226:229], v153 offset:7168
	global_load_lds_dwordx4 v[178:179], off
	v_lshl_add_u64 v[178:179], v[148:149], 0, s[38:39]
	s_add_i32 m0, s47, 0xe000
	s_nop 0
	global_load_lds_dwordx4 v[178:179], off
	s_waitcnt vmcnt(8)
	s_waitcnt lgkmcnt(0)
	s_barrier
	s_waitcnt lgkmcnt(0)
	v_mfma_f32_16x16x32_bf16 v[126:129], v[154:157], v[196:199], v[126:129]
	v_mfma_f32_16x16x32_bf16 v[126:129], v[158:161], v[200:203], v[126:129]
	v_mfma_f32_16x16x32_bf16 v[122:125], v[166:169], v[200:203], v[122:125]
	v_mfma_f32_16x16x32_bf16 v[122:125], v[162:165], v[196:199], v[122:125]
	v_mfma_f32_16x16x32_bf16 v[110:113], v[162:165], v[204:207], v[110:113]
	v_mfma_f32_16x16x32_bf16 v[110:113], v[166:169], v[208:211], v[110:113]
	v_mfma_f32_16x16x32_bf16 v[118:121], v[158:161], v[208:211], v[118:121]
	v_mfma_f32_16x16x32_bf16 v[118:121], v[154:157], v[204:207], v[118:121]
	v_mfma_f32_16x16x32_bf16 v[102:105], v[154:157], v[214:217], v[102:105]
	v_mfma_f32_16x16x32_bf16 v[102:105], v[158:161], v[218:221], v[102:105]
	v_mfma_f32_16x16x32_bf16 v[94:97], v[166:169], v[218:221], v[94:97]
	v_mfma_f32_16x16x32_bf16 v[94:97], v[162:165], v[214:217], v[94:97]
	v_mfma_f32_16x16x32_bf16 v[78:81], v[162:165], v[222:225], v[78:81]
	v_mfma_f32_16x16x32_bf16 v[78:81], v[166:169], v[226:229], v[78:81]
	v_mfma_f32_16x16x32_bf16 v[86:89], v[158:161], v[226:229], v[86:89]
	v_mfma_f32_16x16x32_bf16 v[86:89], v[154:157], v[222:225], v[86:89]
	v_mfma_f32_16x16x32_bf16 v[114:117], v[170:173], v[196:199], v[114:117]
	v_mfma_f32_16x16x32_bf16 v[114:117], v[174:177], v[200:203], v[114:117]
	v_mfma_f32_16x16x32_bf16 v[106:109], v[192:195], v[200:203], v[106:109]
	v_mfma_f32_16x16x32_bf16 v[106:109], v[188:191], v[196:199], v[106:109]
	v_mfma_f32_16x16x32_bf16 v[90:93], v[188:191], v[204:207], v[90:93]
	v_mfma_f32_16x16x32_bf16 v[90:93], v[192:195], v[208:211], v[90:93]
	v_mfma_f32_16x16x32_bf16 v[98:101], v[174:177], v[208:211], v[98:101]
	v_mfma_f32_16x16x32_bf16 v[98:101], v[170:173], v[204:207], v[98:101]
	v_mfma_f32_16x16x32_bf16 v[82:85], v[170:173], v[214:217], v[82:85]
	v_mfma_f32_16x16x32_bf16 v[82:85], v[174:177], v[218:221], v[82:85]
	v_mfma_f32_16x16x32_bf16 v[74:77], v[192:195], v[218:221], v[74:77]
	v_mfma_f32_16x16x32_bf16 v[74:77], v[188:191], v[214:217], v[74:77]
	v_mfma_f32_16x16x32_bf16 v[66:69], v[188:191], v[222:225], v[66:69]
	v_mfma_f32_16x16x32_bf16 v[66:69], v[192:195], v[226:229], v[66:69]
	v_mfma_f32_16x16x32_bf16 v[70:73], v[174:177], v[226:229], v[70:73]
	v_mfma_f32_16x16x32_bf16 v[70:73], v[170:173], v[222:225], v[70:73]
	s_barrier
	s_add_i32 s69, s54, s3
	v_lshl_add_u64 v[178:179], s[42:43], 0, v[136:137]
	s_mov_b32 m0, s69
	ds_read_b128 v[196:199], v153 offset:16384
	ds_read_b128 v[200:203], v153 offset:17408
	ds_read_b128 v[204:207], v153 offset:18432
	ds_read_b128 v[208:211], v153 offset:19456
	ds_read_b128 v[214:217], v153 offset:20480
	ds_read_b128 v[218:221], v153 offset:21504
	ds_read_b128 v[222:225], v153 offset:22528
	ds_read_b128 v[226:229], v153 offset:23552
	global_load_lds_dwordx4 v[178:179], off
	s_add_i32 m0, s69, 0x2000
	s_add_u32 s70, s42, 0x108000
	v_lshl_add_u64 v[230:231], s[42:43], 0, v[140:141]
	s_addc_u32 s71, s43, 0
	s_add_i32 s69, s55, s3
	global_load_lds_dwordx4 v[230:231], off
	v_lshl_add_u64 v[232:233], s[70:71], 0, v[136:137]
	s_mov_b32 m0, s69
	s_nop 0
	global_load_lds_dwordx4 v[232:233], off
	v_lshl_add_u64 v[232:233], s[70:71], 0, v[140:141]
	s_add_i32 m0, s69, 0x2000
	s_nop 0
	global_load_lds_dwordx4 v[232:233], off
	v_lshl_add_u64 v[232:233], s[44:45], 0, v[134:135]
	s_mov_b32 m0, s47
	s_nop 0
	global_load_lds_dwordx4 v[232:233], off
	v_lshl_add_u64 v[232:233], s[44:45], 0, v[138:139]
	s_mov_b32 m0, s48
	s_nop 0
	global_load_lds_dwordx4 v[232:233], off
	s_waitcnt vmcnt(8)
	s_waitcnt lgkmcnt(0)
	s_barrier
	s_waitcnt lgkmcnt(0)
	v_mfma_f32_16x16x32_bf16 v[62:65], v[154:157], v[196:199], v[62:65]
	v_mfma_f32_16x16x32_bf16 v[62:65], v[158:161], v[200:203], v[62:65]
	v_mfma_f32_16x16x32_bf16 v[58:61], v[166:169], v[200:203], v[58:61]
	v_mfma_f32_16x16x32_bf16 v[58:61], v[162:165], v[196:199], v[58:61]
	v_mfma_f32_16x16x32_bf16 v[46:49], v[162:165], v[204:207], v[46:49]
	v_mfma_f32_16x16x32_bf16 v[46:49], v[166:169], v[208:211], v[46:49]
	v_mfma_f32_16x16x32_bf16 v[54:57], v[158:161], v[208:211], v[54:57]
	v_mfma_f32_16x16x32_bf16 v[54:57], v[154:157], v[204:207], v[54:57]
	v_mfma_f32_16x16x32_bf16 v[38:41], v[154:157], v[214:217], v[38:41]
	v_mfma_f32_16x16x32_bf16 v[38:41], v[158:161], v[218:221], v[38:41]
	v_mfma_f32_16x16x32_bf16 v[30:33], v[166:169], v[218:221], v[30:33]
	v_mfma_f32_16x16x32_bf16 v[30:33], v[162:165], v[214:217], v[30:33]
	v_mfma_f32_16x16x32_bf16 v[14:17], v[162:165], v[222:225], v[14:17]
	v_mfma_f32_16x16x32_bf16 v[14:17], v[166:169], v[226:229], v[14:17]
	v_mfma_f32_16x16x32_bf16 v[22:25], v[158:161], v[226:229], v[22:25]
	v_mfma_f32_16x16x32_bf16 v[22:25], v[154:157], v[222:225], v[22:25]
	v_mfma_f32_16x16x32_bf16 v[50:53], v[170:173], v[196:199], v[50:53]
	v_mfma_f32_16x16x32_bf16 v[50:53], v[174:177], v[200:203], v[50:53]
	v_mfma_f32_16x16x32_bf16 v[42:45], v[192:195], v[200:203], v[42:45]
	v_mfma_f32_16x16x32_bf16 v[42:45], v[188:191], v[196:199], v[42:45]
	v_mfma_f32_16x16x32_bf16 v[26:29], v[188:191], v[204:207], v[26:29]
	v_mfma_f32_16x16x32_bf16 v[26:29], v[192:195], v[208:211], v[26:29]
	v_mfma_f32_16x16x32_bf16 v[34:37], v[174:177], v[208:211], v[34:37]
	v_mfma_f32_16x16x32_bf16 v[34:37], v[170:173], v[204:207], v[34:37]
	v_mfma_f32_16x16x32_bf16 v[18:21], v[170:173], v[214:217], v[18:21]
	v_mfma_f32_16x16x32_bf16 v[18:21], v[174:177], v[218:221], v[18:21]
	v_mfma_f32_16x16x32_bf16 v[10:13], v[192:195], v[218:221], v[10:13]
	v_mfma_f32_16x16x32_bf16 v[10:13], v[188:191], v[214:217], v[10:13]
	v_mfma_f32_16x16x32_bf16 v[2:5], v[188:191], v[222:225], v[2:5]
	v_mfma_f32_16x16x32_bf16 v[2:5], v[192:195], v[226:229], v[2:5]
	v_mfma_f32_16x16x32_bf16 v[6:9], v[174:177], v[226:229], v[6:9]
	v_mfma_f32_16x16x32_bf16 v[6:9], v[170:173], v[222:225], v[6:9]
	s_barrier
	s_add_i32 s69, 0, 0x18000
	s_add_i32 s70, 0, 0x1c000
	v_add_u32_e32 v166, s69, v133
	v_add_u32_e32 v187, s70, v133
	ds_read_b128 v[154:157], v166
	ds_read_b128 v[158:161], v166 offset:1024
	ds_read_b128 v[162:165], v166 offset:2048
	ds_read_b128 v[166:169], v166 offset:3072
	ds_read_b128 v[170:173], v187
	ds_read_b128 v[174:177], v187 offset:1024
	ds_read_b128 v[188:191], v187 offset:2048
	ds_read_b128 v[192:195], v187 offset:3072
	s_add_u32 s44, s44, 0x108000
	s_addc_u32 s45, s45, 0
	s_mov_b32 m0, s49
	v_lshl_add_u64 v[232:233], s[44:45], 0, v[134:135]
	ds_read_b128 v[196:199], v153 offset:32768
	ds_read_b128 v[200:203], v153 offset:33792
	ds_read_b128 v[204:207], v153 offset:34816
	ds_read_b128 v[208:211], v153 offset:35840
	ds_read_b128 v[214:217], v153 offset:36864
	ds_read_b128 v[218:221], v153 offset:37888
	ds_read_b128 v[222:225], v153 offset:38912
	ds_read_b128 v[226:229], v153 offset:39936
	global_load_lds_dwordx4 v[232:233], off
	v_lshl_add_u64 v[232:233], s[44:45], 0, v[138:139]
	s_mov_b32 m0, s50
	s_nop 0
	global_load_lds_dwordx4 v[232:233], off
	s_waitcnt vmcnt(8)
	s_waitcnt lgkmcnt(0)
	s_barrier
	s_waitcnt lgkmcnt(0)
	v_mfma_f32_16x16x32_bf16 v[126:129], v[154:157], v[196:199], v[126:129]
	v_mfma_f32_16x16x32_bf16 v[126:129], v[158:161], v[200:203], v[126:129]
	v_mfma_f32_16x16x32_bf16 v[122:125], v[166:169], v[200:203], v[122:125]
	v_mfma_f32_16x16x32_bf16 v[122:125], v[162:165], v[196:199], v[122:125]
	v_mfma_f32_16x16x32_bf16 v[110:113], v[162:165], v[204:207], v[110:113]
	v_mfma_f32_16x16x32_bf16 v[110:113], v[166:169], v[208:211], v[110:113]
	v_mfma_f32_16x16x32_bf16 v[118:121], v[158:161], v[208:211], v[118:121]
	v_mfma_f32_16x16x32_bf16 v[118:121], v[154:157], v[204:207], v[118:121]
	v_mfma_f32_16x16x32_bf16 v[102:105], v[154:157], v[214:217], v[102:105]
	v_mfma_f32_16x16x32_bf16 v[102:105], v[158:161], v[218:221], v[102:105]
	v_mfma_f32_16x16x32_bf16 v[94:97], v[166:169], v[218:221], v[94:97]
	v_mfma_f32_16x16x32_bf16 v[94:97], v[162:165], v[214:217], v[94:97]
	v_mfma_f32_16x16x32_bf16 v[78:81], v[162:165], v[222:225], v[78:81]
	v_mfma_f32_16x16x32_bf16 v[78:81], v[166:169], v[226:229], v[78:81]
	v_mfma_f32_16x16x32_bf16 v[86:89], v[158:161], v[226:229], v[86:89]
	v_mfma_f32_16x16x32_bf16 v[86:89], v[154:157], v[222:225], v[86:89]
	v_mfma_f32_16x16x32_bf16 v[114:117], v[170:173], v[196:199], v[114:117]
	v_mfma_f32_16x16x32_bf16 v[114:117], v[174:177], v[200:203], v[114:117]
	v_mfma_f32_16x16x32_bf16 v[106:109], v[192:195], v[200:203], v[106:109]
	v_mfma_f32_16x16x32_bf16 v[106:109], v[188:191], v[196:199], v[106:109]
	v_mfma_f32_16x16x32_bf16 v[90:93], v[188:191], v[204:207], v[90:93]
	v_mfma_f32_16x16x32_bf16 v[90:93], v[192:195], v[208:211], v[90:93]
	v_mfma_f32_16x16x32_bf16 v[98:101], v[174:177], v[208:211], v[98:101]
	v_mfma_f32_16x16x32_bf16 v[98:101], v[170:173], v[204:207], v[98:101]
	v_mfma_f32_16x16x32_bf16 v[82:85], v[170:173], v[214:217], v[82:85]
	v_mfma_f32_16x16x32_bf16 v[82:85], v[174:177], v[218:221], v[82:85]
	v_mfma_f32_16x16x32_bf16 v[74:77], v[192:195], v[218:221], v[74:77]
	v_mfma_f32_16x16x32_bf16 v[74:77], v[188:191], v[214:217], v[74:77]
	v_mfma_f32_16x16x32_bf16 v[66:69], v[188:191], v[222:225], v[66:69]
	v_mfma_f32_16x16x32_bf16 v[66:69], v[192:195], v[226:229], v[66:69]
	v_mfma_f32_16x16x32_bf16 v[70:73], v[174:177], v[226:229], v[70:73]
	v_mfma_f32_16x16x32_bf16 v[70:73], v[170:173], v[222:225], v[70:73]
	s_barrier
	s_add_i32 s44, s69, s3
	v_lshl_add_u64 v[178:179], v[178:179], 0, s[12:13]
	s_mov_b32 m0, s44
	ds_read_b128 v[196:199], v153 offset:49152
	ds_read_b128 v[200:203], v153 offset:50176
	ds_read_b128 v[204:207], v153 offset:51200
	ds_read_b128 v[208:211], v153 offset:52224
	ds_read_b128 v[214:217], v153 offset:53248
	ds_read_b128 v[218:221], v153 offset:54272
	ds_read_b128 v[222:225], v153 offset:55296
	ds_read_b128 v[226:229], v153 offset:56320
	global_load_lds_dwordx4 v[178:179], off
	s_add_i32 m0, s44, 0x2000
	s_add_u32 s42, s42, 0x108080
	v_lshl_add_u64 v[178:179], v[230:231], 0, s[12:13]
	s_addc_u32 s43, s43, 0
	s_add_i32 s44, s70, s3
	global_load_lds_dwordx4 v[178:179], off
	v_lshl_add_u64 v[178:179], s[42:43], 0, v[136:137]
	s_mov_b32 m0, s44
	s_nop 0
	global_load_lds_dwordx4 v[178:179], off
	v_lshl_add_u64 v[178:179], s[42:43], 0, v[140:141]
	s_add_i32 m0, s44, 0x2000
	s_nop 0
	global_load_lds_dwordx4 v[178:179], off
	v_lshl_add_u64 v[178:179], s[40:41], 0, v[134:135]
	s_mov_b32 m0, s52
	s_nop 0
	global_load_lds_dwordx4 v[178:179], off
	v_lshl_add_u64 v[178:179], s[40:41], 0, v[138:139]
	s_mov_b32 m0, s53
	s_nop 0
	global_load_lds_dwordx4 v[178:179], off
	s_waitcnt vmcnt(8)
	s_waitcnt lgkmcnt(0)
	s_barrier
	s_waitcnt lgkmcnt(0)
	v_mfma_f32_16x16x32_bf16 v[62:65], v[154:157], v[196:199], v[62:65]
	v_mfma_f32_16x16x32_bf16 v[62:65], v[158:161], v[200:203], v[62:65]
	v_mfma_f32_16x16x32_bf16 v[58:61], v[166:169], v[200:203], v[58:61]
	v_mfma_f32_16x16x32_bf16 v[58:61], v[162:165], v[196:199], v[58:61]
	v_mfma_f32_16x16x32_bf16 v[46:49], v[162:165], v[204:207], v[46:49]
	v_mfma_f32_16x16x32_bf16 v[46:49], v[166:169], v[208:211], v[46:49]
	v_mfma_f32_16x16x32_bf16 v[54:57], v[158:161], v[208:211], v[54:57]
	v_mfma_f32_16x16x32_bf16 v[54:57], v[154:157], v[204:207], v[54:57]
	v_mfma_f32_16x16x32_bf16 v[38:41], v[154:157], v[214:217], v[38:41]
	v_mfma_f32_16x16x32_bf16 v[38:41], v[158:161], v[218:221], v[38:41]
	v_mfma_f32_16x16x32_bf16 v[30:33], v[166:169], v[218:221], v[30:33]
	v_mfma_f32_16x16x32_bf16 v[30:33], v[162:165], v[214:217], v[30:33]
	v_mfma_f32_16x16x32_bf16 v[14:17], v[162:165], v[222:225], v[14:17]
	v_mfma_f32_16x16x32_bf16 v[14:17], v[166:169], v[226:229], v[14:17]
	v_mfma_f32_16x16x32_bf16 v[22:25], v[158:161], v[226:229], v[22:25]
	v_mfma_f32_16x16x32_bf16 v[22:25], v[154:157], v[222:225], v[22:25]
	v_mfma_f32_16x16x32_bf16 v[50:53], v[170:173], v[196:199], v[50:53]
	v_mfma_f32_16x16x32_bf16 v[50:53], v[174:177], v[200:203], v[50:53]
	v_mfma_f32_16x16x32_bf16 v[42:45], v[192:195], v[200:203], v[42:45]
	v_mfma_f32_16x16x32_bf16 v[42:45], v[188:191], v[196:199], v[42:45]
	v_mfma_f32_16x16x32_bf16 v[26:29], v[188:191], v[204:207], v[26:29]
	v_mfma_f32_16x16x32_bf16 v[26:29], v[192:195], v[208:211], v[26:29]
	v_mfma_f32_16x16x32_bf16 v[34:37], v[174:177], v[208:211], v[34:37]
	v_mfma_f32_16x16x32_bf16 v[34:37], v[170:173], v[204:207], v[34:37]
	v_mfma_f32_16x16x32_bf16 v[18:21], v[170:173], v[214:217], v[18:21]
	v_mfma_f32_16x16x32_bf16 v[18:21], v[174:177], v[218:221], v[18:21]
	v_mfma_f32_16x16x32_bf16 v[10:13], v[192:195], v[218:221], v[10:13]
	v_mfma_f32_16x16x32_bf16 v[10:13], v[188:191], v[214:217], v[10:13]
	v_mfma_f32_16x16x32_bf16 v[2:5], v[188:191], v[222:225], v[2:5]
	v_mfma_f32_16x16x32_bf16 v[2:5], v[192:195], v[226:229], v[2:5]
	v_mfma_f32_16x16x32_bf16 v[6:9], v[174:177], v[226:229], v[6:9]
	v_mfma_f32_16x16x32_bf16 v[6:9], v[170:173], v[222:225], v[6:9]
	s_barrier
	s_add_i32 s68, s68, 2
	s_add_u32 s38, s38, 0x100
	s_addc_u32 s39, s39, 0
	s_cmp_gt_u32 s68, 61
	s_cbranch_scc0 .LBB0_101
	s_and_b64 vcc, exec, s[20:21]
	s_cbranch_vccz .LBB0_104
	s_barrier

.LBB0_235:
	ds_read_b128 v[156:159], v150
	ds_read_b128 v[160:163], v150 offset:1024
	ds_read_b128 v[164:167], v150 offset:2048
	ds_read_b128 v[168:171], v150 offset:3072
	ds_read_b128 v[172:175], v151
	ds_read_b128 v[176:179], v151 offset:1024
	ds_read_b128 v[180:183], v151 offset:2048
	ds_read_b128 v[184:187], v151 offset:3072
	s_add_u32 s36, s4, s34
	s_addc_u32 s37, s5, s35
	s_add_u32 s40, s36, 0x100
	s_addc_u32 s41, s37, 0
	s_add_u32 s38, s62, s34
	s_addc_u32 s39, s63, s35
	s_add_u32 s36, s36, 0x180
	s_addc_u32 s37, s37, 0
	s_cmpk_eq_i32 s34, 0x1f00
	s_cselect_b32 s37, s61, s37
	s_cselect_b32 s36, s60, s36
	s_cselect_b32 s39, s31, s39
	s_cselect_b32 s38, s30, s38
	s_cselect_b32 s41, s23, s41
	s_cselect_b32 s40, s22, s40
	s_mov_b32 m0, s46
	v_lshl_add_u64 v[222:223], v[146:147], 0, s[34:35]
	ds_read_b128 v[188:191], v152
	ds_read_b128 v[192:195], v152 offset:1024
	ds_read_b128 v[196:199], v152 offset:2048
	ds_read_b128 v[200:203], v152 offset:3072
	ds_read_b128 v[204:207], v152 offset:4096
	ds_read_b128 v[208:211], v152 offset:5120
	ds_read_b128 v[214:217], v152 offset:6144
	ds_read_b128 v[218:221], v152 offset:7168
	global_load_lds_dwordx4 v[222:223], off
	v_lshl_add_u64 v[222:223], v[148:149], 0, s[34:35]
	s_mov_b32 m0, s47
	s_nop 0
	global_load_lds_dwordx4 v[222:223], off
	s_waitcnt vmcnt(8)
	s_waitcnt lgkmcnt(0)
	s_barrier
	s_waitcnt lgkmcnt(0)
	v_mfma_f32_16x16x32_bf16 v[126:129], v[156:159], v[188:191], v[126:129]
	v_mfma_f32_16x16x32_bf16 v[126:129], v[160:163], v[192:195], v[126:129]
	v_mfma_f32_16x16x32_bf16 v[122:125], v[168:171], v[192:195], v[122:125]
	v_mfma_f32_16x16x32_bf16 v[122:125], v[164:167], v[188:191], v[122:125]
	v_mfma_f32_16x16x32_bf16 v[106:109], v[164:167], v[196:199], v[106:109]
	v_mfma_f32_16x16x32_bf16 v[106:109], v[168:171], v[200:203], v[106:109]
	v_mfma_f32_16x16x32_bf16 v[110:113], v[160:163], v[200:203], v[110:113]
	v_mfma_f32_16x16x32_bf16 v[110:113], v[156:159], v[196:199], v[110:113]
	v_mfma_f32_16x16x32_bf16 v[94:97], v[156:159], v[204:207], v[94:97]
	v_mfma_f32_16x16x32_bf16 v[94:97], v[160:163], v[208:211], v[94:97]
	v_mfma_f32_16x16x32_bf16 v[90:93], v[168:171], v[208:211], v[90:93]
	v_mfma_f32_16x16x32_bf16 v[90:93], v[164:167], v[204:207], v[90:93]
	v_mfma_f32_16x16x32_bf16 v[74:77], v[164:167], v[214:217], v[74:77]
	v_mfma_f32_16x16x32_bf16 v[74:77], v[168:171], v[218:221], v[74:77]
	v_mfma_f32_16x16x32_bf16 v[78:81], v[160:163], v[218:221], v[78:81]
	v_mfma_f32_16x16x32_bf16 v[78:81], v[156:159], v[214:217], v[78:81]
	v_mfma_f32_16x16x32_bf16 v[118:121], v[172:175], v[188:191], v[118:121]
	v_mfma_f32_16x16x32_bf16 v[118:121], v[176:179], v[192:195], v[118:121]
	v_mfma_f32_16x16x32_bf16 v[114:117], v[184:187], v[192:195], v[114:117]
	v_mfma_f32_16x16x32_bf16 v[114:117], v[180:183], v[188:191], v[114:117]
	v_mfma_f32_16x16x32_bf16 v[98:101], v[180:183], v[196:199], v[98:101]
	v_mfma_f32_16x16x32_bf16 v[98:101], v[184:187], v[200:203], v[98:101]
	v_mfma_f32_16x16x32_bf16 v[102:105], v[176:179], v[200:203], v[102:105]
	v_mfma_f32_16x16x32_bf16 v[102:105], v[172:175], v[196:199], v[102:105]
	v_mfma_f32_16x16x32_bf16 v[86:89], v[172:175], v[204:207], v[86:89]
	v_mfma_f32_16x16x32_bf16 v[86:89], v[176:179], v[208:211], v[86:89]
	v_mfma_f32_16x16x32_bf16 v[82:85], v[184:187], v[208:211], v[82:85]
	v_mfma_f32_16x16x32_bf16 v[82:85], v[180:183], v[204:207], v[82:85]
	v_mfma_f32_16x16x32_bf16 v[66:69], v[180:183], v[214:217], v[66:69]
	v_mfma_f32_16x16x32_bf16 v[66:69], v[184:187], v[218:221], v[66:69]
	v_mfma_f32_16x16x32_bf16 v[70:73], v[176:179], v[218:221], v[70:73]
	v_mfma_f32_16x16x32_bf16 v[70:73], v[172:175], v[214:217], v[70:73]
	s_barrier
	s_mov_b32 m0, s48
	v_lshl_add_u64 v[222:223], s[38:39], 0, v[132:133]
	s_add_u32 s66, s38, 0x108000
	ds_read_b128 v[188:191], v152 offset:16384
	ds_read_b128 v[192:195], v152 offset:17408
	ds_read_b128 v[196:199], v152 offset:18432
	ds_read_b128 v[200:203], v152 offset:19456
	ds_read_b128 v[204:207], v152 offset:20480
	ds_read_b128 v[208:211], v152 offset:21504
	ds_read_b128 v[214:217], v152 offset:22528
	ds_read_b128 v[218:221], v152 offset:23552
	global_load_lds_dwordx4 v[222:223], off
	v_lshl_add_u64 v[224:225], s[38:39], 0, v[136:137]
	s_mov_b32 m0, s49
	s_addc_u32 s67, s39, 0
	global_load_lds_dwordx4 v[224:225], off
	v_lshl_add_u64 v[226:227], s[66:67], 0, v[132:133]
	s_mov_b32 m0, s50
	s_nop 0
	global_load_lds_dwordx4 v[226:227], off
	v_lshl_add_u64 v[226:227], s[66:67], 0, v[136:137]
	s_mov_b32 m0, s51
	s_nop 0
	global_load_lds_dwordx4 v[226:227], off
	v_lshl_add_u64 v[226:227], s[40:41], 0, v[130:131]
	s_mov_b32 m0, s3
	s_nop 0
	global_load_lds_dwordx4 v[226:227], off
	v_lshl_add_u64 v[226:227], s[40:41], 0, v[134:135]
	s_mov_b32 m0, s33
	s_nop 0
	global_load_lds_dwordx4 v[226:227], off
	s_waitcnt vmcnt(8)
	s_waitcnt lgkmcnt(0)
	s_barrier
	s_waitcnt lgkmcnt(0)
	v_mfma_f32_16x16x32_bf16 v[62:65], v[156:159], v[188:191], v[62:65]
	v_mfma_f32_16x16x32_bf16 v[62:65], v[160:163], v[192:195], v[62:65]
	v_mfma_f32_16x16x32_bf16 v[58:61], v[168:171], v[192:195], v[58:61]
	v_mfma_f32_16x16x32_bf16 v[58:61], v[164:167], v[188:191], v[58:61]
	v_mfma_f32_16x16x32_bf16 v[42:45], v[164:167], v[196:199], v[42:45]
	v_mfma_f32_16x16x32_bf16 v[42:45], v[168:171], v[200:203], v[42:45]
	v_mfma_f32_16x16x32_bf16 v[46:49], v[160:163], v[200:203], v[46:49]
	v_mfma_f32_16x16x32_bf16 v[46:49], v[156:159], v[196:199], v[46:49]
	v_mfma_f32_16x16x32_bf16 v[30:33], v[156:159], v[204:207], v[30:33]
	v_mfma_f32_16x16x32_bf16 v[30:33], v[160:163], v[208:211], v[30:33]
	v_mfma_f32_16x16x32_bf16 v[26:29], v[168:171], v[208:211], v[26:29]
	v_mfma_f32_16x16x32_bf16 v[26:29], v[164:167], v[204:207], v[26:29]
	v_mfma_f32_16x16x32_bf16 v[10:13], v[164:167], v[214:217], v[10:13]
	v_mfma_f32_16x16x32_bf16 v[10:13], v[168:171], v[218:221], v[10:13]
	v_mfma_f32_16x16x32_bf16 v[14:17], v[160:163], v[218:221], v[14:17]
	v_mfma_f32_16x16x32_bf16 v[14:17], v[156:159], v[214:217], v[14:17]
	v_mfma_f32_16x16x32_bf16 v[54:57], v[172:175], v[188:191], v[54:57]
	v_mfma_f32_16x16x32_bf16 v[54:57], v[176:179], v[192:195], v[54:57]
	v_mfma_f32_16x16x32_bf16 v[50:53], v[184:187], v[192:195], v[50:53]
	v_mfma_f32_16x16x32_bf16 v[50:53], v[180:183], v[188:191], v[50:53]
	v_mfma_f32_16x16x32_bf16 v[34:37], v[180:183], v[196:199], v[34:37]
	v_mfma_f32_16x16x32_bf16 v[34:37], v[184:187], v[200:203], v[34:37]
	v_mfma_f32_16x16x32_bf16 v[38:41], v[176:179], v[200:203], v[38:41]
	v_mfma_f32_16x16x32_bf16 v[38:41], v[172:175], v[196:199], v[38:41]
	v_mfma_f32_16x16x32_bf16 v[22:25], v[172:175], v[204:207], v[22:25]
	v_mfma_f32_16x16x32_bf16 v[22:25], v[176:179], v[208:211], v[22:25]
	v_mfma_f32_16x16x32_bf16 v[18:21], v[184:187], v[208:211], v[18:21]
	v_mfma_f32_16x16x32_bf16 v[18:21], v[180:183], v[204:207], v[18:21]
	v_mfma_f32_16x16x32_bf16 v[2:5], v[180:183], v[214:217], v[2:5]
	v_mfma_f32_16x16x32_bf16 v[2:5], v[184:187], v[218:221], v[2:5]
	v_mfma_f32_16x16x32_bf16 v[6:9], v[176:179], v[218:221], v[6:9]
	v_mfma_f32_16x16x32_bf16 v[6:9], v[172:175], v[214:217], v[6:9]
	s_barrier
	ds_read_b128 v[156:159], v153
	ds_read_b128 v[160:163], v153 offset:1024
	ds_read_b128 v[164:167], v153 offset:2048
	ds_read_b128 v[168:171], v153 offset:3072
	ds_read_b128 v[172:175], v154
	ds_read_b128 v[176:179], v154 offset:1024
	ds_read_b128 v[180:183], v154 offset:2048
	ds_read_b128 v[184:187], v154 offset:3072
	s_add_u32 s40, s40, 0x108000
	s_addc_u32 s41, s41, 0
	s_mov_b32 m0, s42
	v_lshl_add_u64 v[226:227], s[40:41], 0, v[130:131]
	ds_read_b128 v[188:191], v152 offset:32768
	ds_read_b128 v[192:195], v152 offset:33792
	ds_read_b128 v[196:199], v152 offset:34816
	ds_read_b128 v[200:203], v152 offset:35840
	ds_read_b128 v[204:207], v152 offset:36864
	ds_read_b128 v[208:211], v152 offset:37888
	ds_read_b128 v[214:217], v152 offset:38912
	ds_read_b128 v[218:221], v152 offset:39936
	global_load_lds_dwordx4 v[226:227], off
	v_lshl_add_u64 v[226:227], s[40:41], 0, v[134:135]
	s_mov_b32 m0, s43
	s_nop 0
	global_load_lds_dwordx4 v[226:227], off
	s_waitcnt vmcnt(8)
	s_waitcnt lgkmcnt(0)
	s_barrier
	s_waitcnt lgkmcnt(0)
	v_mfma_f32_16x16x32_bf16 v[126:129], v[156:159], v[188:191], v[126:129]
	v_mfma_f32_16x16x32_bf16 v[126:129], v[160:163], v[192:195], v[126:129]
	v_mfma_f32_16x16x32_bf16 v[122:125], v[168:171], v[192:195], v[122:125]
	v_mfma_f32_16x16x32_bf16 v[122:125], v[164:167], v[188:191], v[122:125]
	v_mfma_f32_16x16x32_bf16 v[106:109], v[164:167], v[196:199], v[106:109]
	v_mfma_f32_16x16x32_bf16 v[106:109], v[168:171], v[200:203], v[106:109]
	v_mfma_f32_16x16x32_bf16 v[110:113], v[160:163], v[200:203], v[110:113]
	v_mfma_f32_16x16x32_bf16 v[110:113], v[156:159], v[196:199], v[110:113]
	v_mfma_f32_16x16x32_bf16 v[94:97], v[156:159], v[204:207], v[94:97]
	v_mfma_f32_16x16x32_bf16 v[94:97], v[160:163], v[208:211], v[94:97]
	v_mfma_f32_16x16x32_bf16 v[90:93], v[168:171], v[208:211], v[90:93]
	v_mfma_f32_16x16x32_bf16 v[90:93], v[164:167], v[204:207], v[90:93]
	v_mfma_f32_16x16x32_bf16 v[74:77], v[164:167], v[214:217], v[74:77]
	v_mfma_f32_16x16x32_bf16 v[74:77], v[168:171], v[218:221], v[74:77]
	v_mfma_f32_16x16x32_bf16 v[78:81], v[160:163], v[218:221], v[78:81]
	v_mfma_f32_16x16x32_bf16 v[78:81], v[156:159], v[214:217], v[78:81]
	v_mfma_f32_16x16x32_bf16 v[118:121], v[172:175], v[188:191], v[118:121]
	v_mfma_f32_16x16x32_bf16 v[118:121], v[176:179], v[192:195], v[118:121]
	v_mfma_f32_16x16x32_bf16 v[114:117], v[184:187], v[192:195], v[114:117]
	v_mfma_f32_16x16x32_bf16 v[114:117], v[180:183], v[188:191], v[114:117]
	v_mfma_f32_16x16x32_bf16 v[98:101], v[180:183], v[196:199], v[98:101]
	v_mfma_f32_16x16x32_bf16 v[98:101], v[184:187], v[200:203], v[98:101]
	v_mfma_f32_16x16x32_bf16 v[102:105], v[176:179], v[200:203], v[102:105]
	v_mfma_f32_16x16x32_bf16 v[102:105], v[172:175], v[196:199], v[102:105]
	v_mfma_f32_16x16x32_bf16 v[86:89], v[172:175], v[204:207], v[86:89]
	v_mfma_f32_16x16x32_bf16 v[86:89], v[176:179], v[208:211], v[86:89]
	v_mfma_f32_16x16x32_bf16 v[82:85], v[184:187], v[208:211], v[82:85]
	v_mfma_f32_16x16x32_bf16 v[82:85], v[180:183], v[204:207], v[82:85]
	v_mfma_f32_16x16x32_bf16 v[66:69], v[180:183], v[214:217], v[66:69]
	v_mfma_f32_16x16x32_bf16 v[66:69], v[184:187], v[218:221], v[66:69]
	v_mfma_f32_16x16x32_bf16 v[70:73], v[176:179], v[218:221], v[70:73]
	v_mfma_f32_16x16x32_bf16 v[70:73], v[172:175], v[214:217], v[70:73]
	s_barrier
	s_mov_b32 m0, s53
	v_lshl_add_u64 v[222:223], v[222:223], 0, s[16:17]
	s_add_u32 s38, s38, 0x108080
	ds_read_b128 v[188:191], v152 offset:49152
	ds_read_b128 v[192:195], v152 offset:50176
	ds_read_b128 v[196:199], v152 offset:51200
	ds_read_b128 v[200:203], v152 offset:52224
	ds_read_b128 v[204:207], v152 offset:53248
	ds_read_b128 v[208:211], v152 offset:54272
	ds_read_b128 v[214:217], v152 offset:55296
	ds_read_b128 v[218:221], v152 offset:56320
	global_load_lds_dwordx4 v[222:223], off
	v_lshl_add_u64 v[222:223], v[224:225], 0, s[16:17]
	s_mov_b32 m0, s54
	s_addc_u32 s39, s39, 0
	s_add_i32 s40, s52, s2
	global_load_lds_dwordx4 v[222:223], off
	v_lshl_add_u64 v[222:223], s[38:39], 0, v[132:133]
	s_mov_b32 m0, s40
	s_nop 0
	global_load_lds_dwordx4 v[222:223], off
	v_lshl_add_u64 v[222:223], s[38:39], 0, v[136:137]
	s_add_i32 m0, s40, 0x2000
	s_nop 0
	global_load_lds_dwordx4 v[222:223], off
	v_lshl_add_u64 v[222:223], s[36:37], 0, v[130:131]
	s_mov_b32 m0, s44
	s_nop 0
	global_load_lds_dwordx4 v[222:223], off
	v_lshl_add_u64 v[222:223], s[36:37], 0, v[134:135]
	s_mov_b32 m0, s45
	s_nop 0
	global_load_lds_dwordx4 v[222:223], off
	s_waitcnt vmcnt(8)
	s_waitcnt lgkmcnt(0)
	s_barrier
	s_waitcnt lgkmcnt(0)
	v_mfma_f32_16x16x32_bf16 v[62:65], v[156:159], v[188:191], v[62:65]
	v_mfma_f32_16x16x32_bf16 v[62:65], v[160:163], v[192:195], v[62:65]
	v_mfma_f32_16x16x32_bf16 v[58:61], v[168:171], v[192:195], v[58:61]
	v_mfma_f32_16x16x32_bf16 v[58:61], v[164:167], v[188:191], v[58:61]
	v_mfma_f32_16x16x32_bf16 v[42:45], v[164:167], v[196:199], v[42:45]
	v_mfma_f32_16x16x32_bf16 v[42:45], v[168:171], v[200:203], v[42:45]
	v_mfma_f32_16x16x32_bf16 v[46:49], v[160:163], v[200:203], v[46:49]
	v_mfma_f32_16x16x32_bf16 v[46:49], v[156:159], v[196:199], v[46:49]
	v_mfma_f32_16x16x32_bf16 v[30:33], v[156:159], v[204:207], v[30:33]
	v_mfma_f32_16x16x32_bf16 v[30:33], v[160:163], v[208:211], v[30:33]
	v_mfma_f32_16x16x32_bf16 v[26:29], v[168:171], v[208:211], v[26:29]
	v_mfma_f32_16x16x32_bf16 v[26:29], v[164:167], v[204:207], v[26:29]
	v_mfma_f32_16x16x32_bf16 v[10:13], v[164:167], v[214:217], v[10:13]
	v_mfma_f32_16x16x32_bf16 v[10:13], v[168:171], v[218:221], v[10:13]
	v_mfma_f32_16x16x32_bf16 v[14:17], v[160:163], v[218:221], v[14:17]
	v_mfma_f32_16x16x32_bf16 v[14:17], v[156:159], v[214:217], v[14:17]
	v_mfma_f32_16x16x32_bf16 v[54:57], v[172:175], v[188:191], v[54:57]
	v_mfma_f32_16x16x32_bf16 v[54:57], v[176:179], v[192:195], v[54:57]
	v_mfma_f32_16x16x32_bf16 v[50:53], v[184:187], v[192:195], v[50:53]
	v_mfma_f32_16x16x32_bf16 v[50:53], v[180:183], v[188:191], v[50:53]
	v_mfma_f32_16x16x32_bf16 v[34:37], v[180:183], v[196:199], v[34:37]
	v_mfma_f32_16x16x32_bf16 v[34:37], v[184:187], v[200:203], v[34:37]
	v_mfma_f32_16x16x32_bf16 v[38:41], v[176:179], v[200:203], v[38:41]
	v_mfma_f32_16x16x32_bf16 v[38:41], v[172:175], v[196:199], v[38:41]
	v_mfma_f32_16x16x32_bf16 v[22:25], v[172:175], v[204:207], v[22:25]
	v_mfma_f32_16x16x32_bf16 v[22:25], v[176:179], v[208:211], v[22:25]
	v_mfma_f32_16x16x32_bf16 v[18:21], v[184:187], v[208:211], v[18:21]
	v_mfma_f32_16x16x32_bf16 v[18:21], v[180:183], v[204:207], v[18:21]
	v_mfma_f32_16x16x32_bf16 v[2:5], v[180:183], v[214:217], v[2:5]
	v_mfma_f32_16x16x32_bf16 v[2:5], v[184:187], v[218:221], v[2:5]
	v_mfma_f32_16x16x32_bf16 v[6:9], v[176:179], v[218:221], v[6:9]
	v_mfma_f32_16x16x32_bf16 v[6:9], v[172:175], v[214:217], v[6:9]
	s_barrier
	s_add_i32 s64, s64, 2
	s_add_u32 s34, s34, 0x100
	s_addc_u32 s35, s35, 0
	s_cmp_gt_u32 s64, 61
	s_cbranch_scc0 .LBB0_235
	s_and_b64 vcc, exec, s[20:21]
	s_cbranch_vccz .LBB0_238
	s_barrier

.LBB0_434:
	ds_read_b128 v[134:137], v204
	ds_read_b128 v[138:141], v204 offset:1024
	ds_read_b128 v[142:145], v204 offset:2048
	ds_read_b128 v[146:149], v204 offset:3072
	ds_read_b128 v[150:153], v205
	ds_read_b128 v[154:157], v205 offset:1024
	ds_read_b128 v[158:161], v205 offset:2048
	ds_read_b128 v[162:165], v205 offset:3072
	s_add_u32 s34, s22, s30
	s_addc_u32 s35, s23, s31
	s_add_u32 s38, s34, 0x100
	s_addc_u32 s39, s35, 0
	s_add_u32 s36, s60, s30
	s_addc_u32 s37, s61, s31
	s_add_u32 s34, s34, 0x180
	s_addc_u32 s35, s35, 0
	s_cmpk_eq_i32 s30, 0xb00
	s_cselect_b32 s35, s59, s35
	s_cselect_b32 s34, s58, s34
	s_cselect_b32 s37, s21, s37
	s_cselect_b32 s36, s20, s36
	s_cselect_b32 s39, s17, s39
	s_cselect_b32 s38, s16, s38
	v_lshl_add_u64 v[200:201], v[130:131], 0, s[30:31]
	s_add_i32 m0, s3, 0xc000
	ds_read_b128 v[166:169], v206
	ds_read_b128 v[170:173], v206 offset:1024
	ds_read_b128 v[174:177], v206 offset:2048
	ds_read_b128 v[178:181], v206 offset:3072
	ds_read_b128 v[182:185], v206 offset:4096
	ds_read_b128 v[208:211], v206 offset:5120
	ds_read_b128 v[214:217], v206 offset:6144
	ds_read_b128 v[218:221], v206 offset:7168
	global_load_lds_dwordx4 v[200:201], off
	v_lshl_add_u64 v[200:201], v[132:133], 0, s[30:31]
	s_add_i32 m0, s3, 0xe000
	s_nop 0
	global_load_lds_dwordx4 v[200:201], off
	s_waitcnt vmcnt(8)
	s_waitcnt lgkmcnt(0)
	s_barrier
	s_waitcnt lgkmcnt(0)
	v_mfma_f32_16x16x32_bf16 v[126:129], v[134:137], v[166:169], v[126:129]
	v_mfma_f32_16x16x32_bf16 v[126:129], v[138:141], v[170:173], v[126:129]
	v_mfma_f32_16x16x32_bf16 v[122:125], v[146:149], v[170:173], v[122:125]
	v_mfma_f32_16x16x32_bf16 v[122:125], v[142:145], v[166:169], v[122:125]
	v_mfma_f32_16x16x32_bf16 v[106:109], v[142:145], v[174:177], v[106:109]
	v_mfma_f32_16x16x32_bf16 v[106:109], v[146:149], v[178:181], v[106:109]
	v_mfma_f32_16x16x32_bf16 v[110:113], v[138:141], v[178:181], v[110:113]
	v_mfma_f32_16x16x32_bf16 v[110:113], v[134:137], v[174:177], v[110:113]
	v_mfma_f32_16x16x32_bf16 v[94:97], v[134:137], v[182:185], v[94:97]
	v_mfma_f32_16x16x32_bf16 v[94:97], v[138:141], v[208:211], v[94:97]
	v_mfma_f32_16x16x32_bf16 v[90:93], v[146:149], v[208:211], v[90:93]
	v_mfma_f32_16x16x32_bf16 v[90:93], v[142:145], v[182:185], v[90:93]
	v_mfma_f32_16x16x32_bf16 v[74:77], v[142:145], v[214:217], v[74:77]
	v_mfma_f32_16x16x32_bf16 v[74:77], v[146:149], v[218:221], v[74:77]
	v_mfma_f32_16x16x32_bf16 v[78:81], v[138:141], v[218:221], v[78:81]
	v_mfma_f32_16x16x32_bf16 v[78:81], v[134:137], v[214:217], v[78:81]
	v_mfma_f32_16x16x32_bf16 v[118:121], v[150:153], v[166:169], v[118:121]
	v_mfma_f32_16x16x32_bf16 v[118:121], v[154:157], v[170:173], v[118:121]
	v_mfma_f32_16x16x32_bf16 v[114:117], v[162:165], v[170:173], v[114:117]
	v_mfma_f32_16x16x32_bf16 v[114:117], v[158:161], v[166:169], v[114:117]
	v_mfma_f32_16x16x32_bf16 v[98:101], v[158:161], v[174:177], v[98:101]
	v_mfma_f32_16x16x32_bf16 v[98:101], v[162:165], v[178:181], v[98:101]
	v_mfma_f32_16x16x32_bf16 v[102:105], v[154:157], v[178:181], v[102:105]
	v_mfma_f32_16x16x32_bf16 v[102:105], v[150:153], v[174:177], v[102:105]
	v_mfma_f32_16x16x32_bf16 v[86:89], v[150:153], v[182:185], v[86:89]
	v_mfma_f32_16x16x32_bf16 v[86:89], v[154:157], v[208:211], v[86:89]
	v_mfma_f32_16x16x32_bf16 v[82:85], v[162:165], v[208:211], v[82:85]
	v_mfma_f32_16x16x32_bf16 v[82:85], v[158:161], v[182:185], v[82:85]
	v_mfma_f32_16x16x32_bf16 v[66:69], v[158:161], v[214:217], v[66:69]
	v_mfma_f32_16x16x32_bf16 v[66:69], v[162:165], v[218:221], v[66:69]
	v_mfma_f32_16x16x32_bf16 v[70:73], v[154:157], v[218:221], v[70:73]
	v_mfma_f32_16x16x32_bf16 v[70:73], v[150:153], v[214:217], v[70:73]
	s_barrier
	s_add_i32 s63, s52, s2
	v_lshl_add_u64 v[200:201], s[36:37], 0, v[188:189]
	s_mov_b32 m0, s63
	ds_read_b128 v[166:169], v206 offset:16384
	ds_read_b128 v[170:173], v206 offset:17408
	ds_read_b128 v[174:177], v206 offset:18432
	ds_read_b128 v[178:181], v206 offset:19456
	ds_read_b128 v[182:185], v206 offset:20480
	ds_read_b128 v[208:211], v206 offset:21504
	ds_read_b128 v[214:217], v206 offset:22528
	ds_read_b128 v[218:221], v206 offset:23552
	global_load_lds_dwordx4 v[200:201], off
	s_add_i32 m0, s63, 0x2000
	s_add_u32 s64, s36, 0x68000
	v_lshl_add_u64 v[222:223], s[36:37], 0, v[192:193]
	s_addc_u32 s65, s37, 0
	s_add_i32 s63, s53, s2
	global_load_lds_dwordx4 v[222:223], off
	v_lshl_add_u64 v[224:225], s[64:65], 0, v[188:189]
	s_mov_b32 m0, s63
	s_nop 0
	global_load_lds_dwordx4 v[224:225], off
	v_lshl_add_u64 v[224:225], s[64:65], 0, v[192:193]
	s_add_i32 m0, s63, 0x2000
	s_nop 0
	global_load_lds_dwordx4 v[224:225], off
	v_lshl_add_u64 v[224:225], s[38:39], 0, v[186:187]
	s_mov_b32 m0, s3
	s_nop 0
	global_load_lds_dwordx4 v[224:225], off
	v_lshl_add_u64 v[224:225], s[38:39], 0, v[190:191]
	s_mov_b32 m0, s33
	s_nop 0
	global_load_lds_dwordx4 v[224:225], off
	s_waitcnt vmcnt(8)
	s_waitcnt lgkmcnt(0)
	s_barrier
	s_waitcnt lgkmcnt(0)
	v_mfma_f32_16x16x32_bf16 v[62:65], v[134:137], v[166:169], v[62:65]
	v_mfma_f32_16x16x32_bf16 v[62:65], v[138:141], v[170:173], v[62:65]
	v_mfma_f32_16x16x32_bf16 v[58:61], v[146:149], v[170:173], v[58:61]
	v_mfma_f32_16x16x32_bf16 v[58:61], v[142:145], v[166:169], v[58:61]
	v_mfma_f32_16x16x32_bf16 v[42:45], v[142:145], v[174:177], v[42:45]
	v_mfma_f32_16x16x32_bf16 v[42:45], v[146:149], v[178:181], v[42:45]
	v_mfma_f32_16x16x32_bf16 v[46:49], v[138:141], v[178:181], v[46:49]
	v_mfma_f32_16x16x32_bf16 v[46:49], v[134:137], v[174:177], v[46:49]
	v_mfma_f32_16x16x32_bf16 v[30:33], v[134:137], v[182:185], v[30:33]
	v_mfma_f32_16x16x32_bf16 v[30:33], v[138:141], v[208:211], v[30:33]
	v_mfma_f32_16x16x32_bf16 v[26:29], v[146:149], v[208:211], v[26:29]
	v_mfma_f32_16x16x32_bf16 v[26:29], v[142:145], v[182:185], v[26:29]
	v_mfma_f32_16x16x32_bf16 v[10:13], v[142:145], v[214:217], v[10:13]
	v_mfma_f32_16x16x32_bf16 v[10:13], v[146:149], v[218:221], v[10:13]
	v_mfma_f32_16x16x32_bf16 v[14:17], v[138:141], v[218:221], v[14:17]
	v_mfma_f32_16x16x32_bf16 v[14:17], v[134:137], v[214:217], v[14:17]
	v_mfma_f32_16x16x32_bf16 v[54:57], v[150:153], v[166:169], v[54:57]
	v_mfma_f32_16x16x32_bf16 v[54:57], v[154:157], v[170:173], v[54:57]
	v_mfma_f32_16x16x32_bf16 v[50:53], v[162:165], v[170:173], v[50:53]
	v_mfma_f32_16x16x32_bf16 v[50:53], v[158:161], v[166:169], v[50:53]
	v_mfma_f32_16x16x32_bf16 v[34:37], v[158:161], v[174:177], v[34:37]
	v_mfma_f32_16x16x32_bf16 v[34:37], v[162:165], v[178:181], v[34:37]
	v_mfma_f32_16x16x32_bf16 v[38:41], v[154:157], v[178:181], v[38:41]
	v_mfma_f32_16x16x32_bf16 v[38:41], v[150:153], v[174:177], v[38:41]
	v_mfma_f32_16x16x32_bf16 v[22:25], v[150:153], v[182:185], v[22:25]
	v_mfma_f32_16x16x32_bf16 v[22:25], v[154:157], v[208:211], v[22:25]
	v_mfma_f32_16x16x32_bf16 v[18:21], v[162:165], v[208:211], v[18:21]
	v_mfma_f32_16x16x32_bf16 v[18:21], v[158:161], v[182:185], v[18:21]
	v_mfma_f32_16x16x32_bf16 v[2:5], v[158:161], v[214:217], v[2:5]
	v_mfma_f32_16x16x32_bf16 v[2:5], v[162:165], v[218:221], v[2:5]
	v_mfma_f32_16x16x32_bf16 v[6:9], v[154:157], v[218:221], v[6:9]
	v_mfma_f32_16x16x32_bf16 v[6:9], v[150:153], v[214:217], v[6:9]
	s_barrier
	s_add_i32 s63, 0, 0x18000
	s_add_i32 s64, 0, 0x1c000
	v_add_u32_e32 v146, s63, v202
	v_add_u32_e32 v162, s64, v202
	ds_read_b128 v[134:137], v146
	ds_read_b128 v[138:141], v146 offset:1024
	ds_read_b128 v[142:145], v146 offset:2048
	ds_read_b128 v[146:149], v146 offset:3072
	ds_read_b128 v[150:153], v162
	ds_read_b128 v[154:157], v162 offset:1024
	ds_read_b128 v[158:161], v162 offset:2048
	ds_read_b128 v[162:165], v162 offset:3072
	s_add_u32 s38, s38, 0x188000
	s_addc_u32 s39, s39, 0
	s_mov_b32 m0, s40
	v_lshl_add_u64 v[224:225], s[38:39], 0, v[186:187]
	ds_read_b128 v[166:169], v206 offset:32768
	ds_read_b128 v[170:173], v206 offset:33792
	ds_read_b128 v[174:177], v206 offset:34816
	ds_read_b128 v[178:181], v206 offset:35840
	ds_read_b128 v[182:185], v206 offset:36864
	ds_read_b128 v[208:211], v206 offset:37888
	ds_read_b128 v[214:217], v206 offset:38912
	ds_read_b128 v[218:221], v206 offset:39936
	global_load_lds_dwordx4 v[224:225], off
	v_lshl_add_u64 v[224:225], s[38:39], 0, v[190:191]
	s_mov_b32 m0, s41
	s_nop 0
	global_load_lds_dwordx4 v[224:225], off
	s_waitcnt vmcnt(8)
	s_waitcnt lgkmcnt(0)
	s_barrier
	s_waitcnt lgkmcnt(0)
	v_mfma_f32_16x16x32_bf16 v[126:129], v[134:137], v[166:169], v[126:129]
	v_mfma_f32_16x16x32_bf16 v[126:129], v[138:141], v[170:173], v[126:129]
	v_mfma_f32_16x16x32_bf16 v[122:125], v[146:149], v[170:173], v[122:125]
	v_mfma_f32_16x16x32_bf16 v[122:125], v[142:145], v[166:169], v[122:125]
	v_mfma_f32_16x16x32_bf16 v[106:109], v[142:145], v[174:177], v[106:109]
	v_mfma_f32_16x16x32_bf16 v[106:109], v[146:149], v[178:181], v[106:109]
	v_mfma_f32_16x16x32_bf16 v[110:113], v[138:141], v[178:181], v[110:113]
	v_mfma_f32_16x16x32_bf16 v[110:113], v[134:137], v[174:177], v[110:113]
	v_mfma_f32_16x16x32_bf16 v[94:97], v[134:137], v[182:185], v[94:97]
	v_mfma_f32_16x16x32_bf16 v[94:97], v[138:141], v[208:211], v[94:97]
	v_mfma_f32_16x16x32_bf16 v[90:93], v[146:149], v[208:211], v[90:93]
	v_mfma_f32_16x16x32_bf16 v[90:93], v[142:145], v[182:185], v[90:93]
	v_mfma_f32_16x16x32_bf16 v[74:77], v[142:145], v[214:217], v[74:77]
	v_mfma_f32_16x16x32_bf16 v[74:77], v[146:149], v[218:221], v[74:77]
	v_mfma_f32_16x16x32_bf16 v[78:81], v[138:141], v[218:221], v[78:81]
	v_mfma_f32_16x16x32_bf16 v[78:81], v[134:137], v[214:217], v[78:81]
	v_mfma_f32_16x16x32_bf16 v[118:121], v[150:153], v[166:169], v[118:121]
	v_mfma_f32_16x16x32_bf16 v[118:121], v[154:157], v[170:173], v[118:121]
	v_mfma_f32_16x16x32_bf16 v[114:117], v[162:165], v[170:173], v[114:117]
	v_mfma_f32_16x16x32_bf16 v[114:117], v[158:161], v[166:169], v[114:117]
	v_mfma_f32_16x16x32_bf16 v[98:101], v[158:161], v[174:177], v[98:101]
	v_mfma_f32_16x16x32_bf16 v[98:101], v[162:165], v[178:181], v[98:101]
	v_mfma_f32_16x16x32_bf16 v[102:105], v[154:157], v[178:181], v[102:105]
	v_mfma_f32_16x16x32_bf16 v[102:105], v[150:153], v[174:177], v[102:105]
	v_mfma_f32_16x16x32_bf16 v[86:89], v[150:153], v[182:185], v[86:89]
	v_mfma_f32_16x16x32_bf16 v[86:89], v[154:157], v[208:211], v[86:89]
	v_mfma_f32_16x16x32_bf16 v[82:85], v[162:165], v[208:211], v[82:85]
	v_mfma_f32_16x16x32_bf16 v[82:85], v[158:161], v[182:185], v[82:85]
	v_mfma_f32_16x16x32_bf16 v[66:69], v[158:161], v[214:217], v[66:69]
	v_mfma_f32_16x16x32_bf16 v[66:69], v[162:165], v[218:221], v[66:69]
	v_mfma_f32_16x16x32_bf16 v[70:73], v[154:157], v[218:221], v[70:73]
	v_mfma_f32_16x16x32_bf16 v[70:73], v[150:153], v[214:217], v[70:73]
	s_barrier
	s_add_i32 s38, s63, s2
	v_lshl_add_u64 v[200:201], v[200:201], 0, s[12:13]
	s_mov_b32 m0, s38
	ds_read_b128 v[166:169], v206 offset:49152
	ds_read_b128 v[170:173], v206 offset:50176
	ds_read_b128 v[174:177], v206 offset:51200
	ds_read_b128 v[178:181], v206 offset:52224
	ds_read_b128 v[182:185], v206 offset:53248
	ds_read_b128 v[208:211], v206 offset:54272
	ds_read_b128 v[214:217], v206 offset:55296
	ds_read_b128 v[218:221], v206 offset:56320
	global_load_lds_dwordx4 v[200:201], off
	s_add_i32 m0, s38, 0x2000
	s_add_u32 s36, s36, 0x68080
	v_lshl_add_u64 v[200:201], v[222:223], 0, s[12:13]
	s_addc_u32 s37, s37, 0
	s_add_i32 s38, s64, s2
	global_load_lds_dwordx4 v[200:201], off
	v_lshl_add_u64 v[200:201], s[36:37], 0, v[188:189]
	s_mov_b32 m0, s38
	s_nop 0
	global_load_lds_dwordx4 v[200:201], off
	v_lshl_add_u64 v[200:201], s[36:37], 0, v[192:193]
	s_add_i32 m0, s38, 0x2000
	s_nop 0
	global_load_lds_dwordx4 v[200:201], off
	v_lshl_add_u64 v[200:201], s[34:35], 0, v[186:187]
	s_mov_b32 m0, s50
	s_nop 0
	global_load_lds_dwordx4 v[200:201], off
	v_lshl_add_u64 v[200:201], s[34:35], 0, v[190:191]
	s_mov_b32 m0, s51
	s_nop 0
	global_load_lds_dwordx4 v[200:201], off
	s_waitcnt vmcnt(8)
	s_waitcnt lgkmcnt(0)
	s_barrier
	s_waitcnt lgkmcnt(0)
	v_mfma_f32_16x16x32_bf16 v[62:65], v[134:137], v[166:169], v[62:65]
	v_mfma_f32_16x16x32_bf16 v[62:65], v[138:141], v[170:173], v[62:65]
	v_mfma_f32_16x16x32_bf16 v[58:61], v[146:149], v[170:173], v[58:61]
	v_mfma_f32_16x16x32_bf16 v[58:61], v[142:145], v[166:169], v[58:61]
	v_mfma_f32_16x16x32_bf16 v[42:45], v[142:145], v[174:177], v[42:45]
	v_mfma_f32_16x16x32_bf16 v[42:45], v[146:149], v[178:181], v[42:45]
	v_mfma_f32_16x16x32_bf16 v[46:49], v[138:141], v[178:181], v[46:49]
	v_mfma_f32_16x16x32_bf16 v[46:49], v[134:137], v[174:177], v[46:49]
	v_mfma_f32_16x16x32_bf16 v[30:33], v[134:137], v[182:185], v[30:33]
	v_mfma_f32_16x16x32_bf16 v[30:33], v[138:141], v[208:211], v[30:33]
	v_mfma_f32_16x16x32_bf16 v[26:29], v[146:149], v[208:211], v[26:29]
	v_mfma_f32_16x16x32_bf16 v[26:29], v[142:145], v[182:185], v[26:29]
	v_mfma_f32_16x16x32_bf16 v[10:13], v[142:145], v[214:217], v[10:13]
	v_mfma_f32_16x16x32_bf16 v[10:13], v[146:149], v[218:221], v[10:13]
	v_mfma_f32_16x16x32_bf16 v[14:17], v[138:141], v[218:221], v[14:17]
	v_mfma_f32_16x16x32_bf16 v[14:17], v[134:137], v[214:217], v[14:17]
	v_mfma_f32_16x16x32_bf16 v[54:57], v[150:153], v[166:169], v[54:57]
	v_mfma_f32_16x16x32_bf16 v[54:57], v[154:157], v[170:173], v[54:57]
	v_mfma_f32_16x16x32_bf16 v[50:53], v[162:165], v[170:173], v[50:53]
	v_mfma_f32_16x16x32_bf16 v[50:53], v[158:161], v[166:169], v[50:53]
	v_mfma_f32_16x16x32_bf16 v[34:37], v[158:161], v[174:177], v[34:37]
	v_mfma_f32_16x16x32_bf16 v[34:37], v[162:165], v[178:181], v[34:37]
	v_mfma_f32_16x16x32_bf16 v[38:41], v[154:157], v[178:181], v[38:41]
	v_mfma_f32_16x16x32_bf16 v[38:41], v[150:153], v[174:177], v[38:41]
	v_mfma_f32_16x16x32_bf16 v[22:25], v[150:153], v[182:185], v[22:25]
	v_mfma_f32_16x16x32_bf16 v[22:25], v[154:157], v[208:211], v[22:25]
	v_mfma_f32_16x16x32_bf16 v[18:21], v[162:165], v[208:211], v[18:21]
	v_mfma_f32_16x16x32_bf16 v[18:21], v[158:161], v[182:185], v[18:21]
	v_mfma_f32_16x16x32_bf16 v[2:5], v[158:161], v[214:217], v[2:5]
	v_mfma_f32_16x16x32_bf16 v[2:5], v[162:165], v[218:221], v[2:5]
	v_mfma_f32_16x16x32_bf16 v[6:9], v[154:157], v[218:221], v[6:9]
	v_mfma_f32_16x16x32_bf16 v[6:9], v[150:153], v[214:217], v[6:9]
	s_barrier
	s_add_i32 s62, s62, 2
	s_add_u32 s30, s30, 0x100
	s_addc_u32 s31, s31, 0
	s_cmp_gt_u32 s62, 21
	s_cbranch_scc0 .LBB0_434
	s_and_b64 vcc, exec, s[14:15]
	s_cbranch_vccz .LBB0_437
	s_barrier

.LBB0_519:
	s_add_i32 s39, s56, 0xfffe8000
	s_and_b32 s38, s36, 0x100
	s_and_b32 s39, s39, 0x3e0000
	s_or_b32 s38, s38, s39
	s_add_u32 s57, s34, s38
	s_addc_u32 s59, s35, 0
	s_add_u32 s38, s36, 0x100
	s_addc_u32 s39, s37, 0
	s_add_i32 s41, s56, 0xffff8000
	s_and_b32 s40, s38, 0x100
	s_and_b32 s41, s41, 0x7e0000
	s_or_b32 s40, s41, s40
	s_add_u32 s40, s34, s40
	s_addc_u32 s41, s35, 0
	s_add_u32 s58, s53, s36
	s_addc_u32 s37, s54, s37
	s_add_i32 s42, s36, 0x180
	s_and_b32 s42, s42, 0x180
	s_and_b32 s43, s56, 0x7e0000
	s_or_b32 s42, s43, s42
	s_add_u32 s60, s34, s42
	s_addc_u32 s61, s35, 0
	s_cmpk_eq_i32 s36, 0x3f00
	s_cselect_b32 s43, s1, s41
	s_cselect_b32 s42, s21, s40
	s_cselect_b32 s41, s23, s37
	s_cselect_b32 s40, s22, s58
	s_cselect_b32 s37, s52, s61
	s_cselect_b32 s36, s31, s60
	s_add_i32 s60, 0, 0x10000
	v_add_u32_e32 v1, s60, v199
	ds_read_b128 v[130:133], v1
	ds_read_b128 v[134:137], v1 offset:1024
	ds_read_b128 v[138:141], v1 offset:2048
	ds_read_b128 v[142:145], v1 offset:3072
	ds_read_b128 v[146:149], v201
	ds_read_b128 v[150:153], v201 offset:1024
	ds_read_b128 v[154:157], v201 offset:2048
	ds_read_b128 v[158:161], v201 offset:3072
	s_add_u32 s58, s57, 0x10080
	s_addc_u32 s59, s59, 0
	v_lshl_add_u64 v[208:209], s[58:59], 0, v[178:179]
	s_add_i32 m0, s3, 0xc000
	ds_read_b128 v[162:165], v202
	ds_read_b128 v[166:169], v202 offset:1024
	ds_read_b128 v[170:173], v202 offset:2048
	ds_read_b128 v[174:177], v202 offset:3072
	ds_read_b128 v[186:189], v202 offset:4096
	ds_read_b128 v[190:193], v202 offset:5120
	ds_read_b128 v[194:197], v202 offset:6144
	ds_read_b128 v[204:207], v202 offset:7168
	global_load_lds_dwordx4 v[208:209], off
	v_lshl_add_u64 v[208:209], s[58:59], 0, v[182:183]
	s_add_i32 m0, s3, 0xe000
	s_nop 0
	global_load_lds_dwordx4 v[208:209], off
	s_waitcnt vmcnt(8)
	s_waitcnt lgkmcnt(0)
	s_barrier
	s_waitcnt lgkmcnt(0)
	v_mfma_f32_16x16x32_bf16 v[126:129], v[130:133], v[162:165], v[126:129]
	v_mfma_f32_16x16x32_bf16 v[126:129], v[134:137], v[166:169], v[126:129]
	v_mfma_f32_16x16x32_bf16 v[122:125], v[142:145], v[166:169], v[122:125]
	v_mfma_f32_16x16x32_bf16 v[122:125], v[138:141], v[162:165], v[122:125]
	v_mfma_f32_16x16x32_bf16 v[106:109], v[138:141], v[170:173], v[106:109]
	v_mfma_f32_16x16x32_bf16 v[106:109], v[142:145], v[174:177], v[106:109]
	v_mfma_f32_16x16x32_bf16 v[110:113], v[134:137], v[174:177], v[110:113]
	v_mfma_f32_16x16x32_bf16 v[110:113], v[130:133], v[170:173], v[110:113]
	v_mfma_f32_16x16x32_bf16 v[94:97], v[130:133], v[186:189], v[94:97]
	v_mfma_f32_16x16x32_bf16 v[94:97], v[134:137], v[190:193], v[94:97]
	v_mfma_f32_16x16x32_bf16 v[90:93], v[142:145], v[190:193], v[90:93]
	v_mfma_f32_16x16x32_bf16 v[90:93], v[138:141], v[186:189], v[90:93]
	v_mfma_f32_16x16x32_bf16 v[74:77], v[138:141], v[194:197], v[74:77]
	v_mfma_f32_16x16x32_bf16 v[74:77], v[142:145], v[204:207], v[74:77]
	v_mfma_f32_16x16x32_bf16 v[78:81], v[134:137], v[204:207], v[78:81]
	v_mfma_f32_16x16x32_bf16 v[78:81], v[130:133], v[194:197], v[78:81]
	v_mfma_f32_16x16x32_bf16 v[118:121], v[146:149], v[162:165], v[118:121]
	v_mfma_f32_16x16x32_bf16 v[118:121], v[150:153], v[166:169], v[118:121]
	v_mfma_f32_16x16x32_bf16 v[114:117], v[158:161], v[166:169], v[114:117]
	v_mfma_f32_16x16x32_bf16 v[114:117], v[154:157], v[162:165], v[114:117]
	v_mfma_f32_16x16x32_bf16 v[98:101], v[154:157], v[170:173], v[98:101]
	v_mfma_f32_16x16x32_bf16 v[98:101], v[158:161], v[174:177], v[98:101]
	v_mfma_f32_16x16x32_bf16 v[102:105], v[150:153], v[174:177], v[102:105]
	v_mfma_f32_16x16x32_bf16 v[102:105], v[146:149], v[170:173], v[102:105]
	v_mfma_f32_16x16x32_bf16 v[86:89], v[146:149], v[186:189], v[86:89]
	v_mfma_f32_16x16x32_bf16 v[86:89], v[150:153], v[190:193], v[86:89]
	v_mfma_f32_16x16x32_bf16 v[82:85], v[158:161], v[190:193], v[82:85]
	v_mfma_f32_16x16x32_bf16 v[82:85], v[154:157], v[186:189], v[82:85]
	v_mfma_f32_16x16x32_bf16 v[66:69], v[154:157], v[194:197], v[66:69]
	v_mfma_f32_16x16x32_bf16 v[66:69], v[158:161], v[204:207], v[66:69]
	v_mfma_f32_16x16x32_bf16 v[70:73], v[150:153], v[204:207], v[70:73]
	v_mfma_f32_16x16x32_bf16 v[70:73], v[146:149], v[194:197], v[70:73]
	s_barrier
	s_add_i32 s57, s60, s2
	v_lshl_add_u64 v[208:209], s[40:41], 0, v[180:181]
	s_mov_b32 m0, s57
	ds_read_b128 v[162:165], v202 offset:16384
	ds_read_b128 v[166:169], v202 offset:17408
	ds_read_b128 v[170:173], v202 offset:18432
	ds_read_b128 v[174:177], v202 offset:19456
	ds_read_b128 v[186:189], v202 offset:20480
	ds_read_b128 v[190:193], v202 offset:21504
	ds_read_b128 v[194:197], v202 offset:22528
	ds_read_b128 v[204:207], v202 offset:23552
	global_load_lds_dwordx4 v[208:209], off
	s_add_i32 m0, s57, 0x2000
	s_add_u32 s58, s40, 0x208000
	v_lshl_add_u64 v[210:211], s[40:41], 0, v[184:185]
	s_addc_u32 s59, s41, 0
	s_add_i32 s57, s49, s2
	global_load_lds_dwordx4 v[210:211], off
	v_lshl_add_u64 v[214:215], s[58:59], 0, v[180:181]
	s_mov_b32 m0, s57
	s_nop 0
	global_load_lds_dwordx4 v[214:215], off
	v_lshl_add_u64 v[214:215], s[58:59], 0, v[184:185]
	s_add_i32 m0, s57, 0x2000
	s_nop 0
	global_load_lds_dwordx4 v[214:215], off
	v_lshl_add_u64 v[214:215], s[42:43], 0, v[178:179]
	s_mov_b32 m0, s3
	s_nop 0
	global_load_lds_dwordx4 v[214:215], off
	v_lshl_add_u64 v[214:215], s[42:43], 0, v[182:183]
	s_mov_b32 m0, s33
	s_nop 0
	global_load_lds_dwordx4 v[214:215], off
	s_waitcnt vmcnt(8)
	s_waitcnt lgkmcnt(0)
	s_barrier
	s_waitcnt lgkmcnt(0)
	v_mfma_f32_16x16x32_bf16 v[62:65], v[130:133], v[162:165], v[62:65]
	v_mfma_f32_16x16x32_bf16 v[62:65], v[134:137], v[166:169], v[62:65]
	v_mfma_f32_16x16x32_bf16 v[58:61], v[142:145], v[166:169], v[58:61]
	v_mfma_f32_16x16x32_bf16 v[58:61], v[138:141], v[162:165], v[58:61]
	v_mfma_f32_16x16x32_bf16 v[42:45], v[138:141], v[170:173], v[42:45]
	v_mfma_f32_16x16x32_bf16 v[42:45], v[142:145], v[174:177], v[42:45]
	v_mfma_f32_16x16x32_bf16 v[46:49], v[134:137], v[174:177], v[46:49]
	v_mfma_f32_16x16x32_bf16 v[46:49], v[130:133], v[170:173], v[46:49]
	v_mfma_f32_16x16x32_bf16 v[30:33], v[130:133], v[186:189], v[30:33]
	v_mfma_f32_16x16x32_bf16 v[30:33], v[134:137], v[190:193], v[30:33]
	v_mfma_f32_16x16x32_bf16 v[26:29], v[142:145], v[190:193], v[26:29]
	v_mfma_f32_16x16x32_bf16 v[26:29], v[138:141], v[186:189], v[26:29]
	v_mfma_f32_16x16x32_bf16 v[10:13], v[138:141], v[194:197], v[10:13]
	v_mfma_f32_16x16x32_bf16 v[10:13], v[142:145], v[204:207], v[10:13]
	v_mfma_f32_16x16x32_bf16 v[14:17], v[134:137], v[204:207], v[14:17]
	v_mfma_f32_16x16x32_bf16 v[14:17], v[130:133], v[194:197], v[14:17]
	v_mfma_f32_16x16x32_bf16 v[54:57], v[146:149], v[162:165], v[54:57]
	v_mfma_f32_16x16x32_bf16 v[54:57], v[150:153], v[166:169], v[54:57]
	v_mfma_f32_16x16x32_bf16 v[50:53], v[158:161], v[166:169], v[50:53]
	v_mfma_f32_16x16x32_bf16 v[50:53], v[154:157], v[162:165], v[50:53]
	v_mfma_f32_16x16x32_bf16 v[34:37], v[154:157], v[170:173], v[34:37]
	v_mfma_f32_16x16x32_bf16 v[34:37], v[158:161], v[174:177], v[34:37]
	v_mfma_f32_16x16x32_bf16 v[38:41], v[150:153], v[174:177], v[38:41]
	v_mfma_f32_16x16x32_bf16 v[38:41], v[146:149], v[170:173], v[38:41]
	v_mfma_f32_16x16x32_bf16 v[22:25], v[146:149], v[186:189], v[22:25]
	v_mfma_f32_16x16x32_bf16 v[22:25], v[150:153], v[190:193], v[22:25]
	v_mfma_f32_16x16x32_bf16 v[18:21], v[158:161], v[190:193], v[18:21]
	v_mfma_f32_16x16x32_bf16 v[18:21], v[154:157], v[186:189], v[18:21]
	v_mfma_f32_16x16x32_bf16 v[2:5], v[154:157], v[194:197], v[2:5]
	v_mfma_f32_16x16x32_bf16 v[2:5], v[158:161], v[204:207], v[2:5]
	v_mfma_f32_16x16x32_bf16 v[6:9], v[150:153], v[204:207], v[6:9]
	v_mfma_f32_16x16x32_bf16 v[6:9], v[146:149], v[194:197], v[6:9]
	s_barrier
	s_add_i32 s57, 0, 0x18000
	v_add_u32_e32 v1, s57, v199
	s_add_i32 s58, 0, 0x1c000
	ds_read_b128 v[130:133], v1
	ds_read_b128 v[134:137], v1 offset:1024
	ds_read_b128 v[138:141], v1 offset:2048
	ds_read_b128 v[142:145], v1 offset:3072
	v_add_u32_e32 v1, s58, v199
	ds_read_b128 v[146:149], v1
	ds_read_b128 v[150:153], v1 offset:1024
	ds_read_b128 v[154:157], v1 offset:2048
	ds_read_b128 v[158:161], v1 offset:3072
	s_add_u32 s42, s42, 0x10000
	s_addc_u32 s43, s43, 0
	s_mov_b32 m0, s44
	v_lshl_add_u64 v[214:215], s[42:43], 0, v[178:179]
	ds_read_b128 v[162:165], v202 offset:32768
	ds_read_b128 v[166:169], v202 offset:33792
	ds_read_b128 v[170:173], v202 offset:34816
	ds_read_b128 v[174:177], v202 offset:35840
	ds_read_b128 v[186:189], v202 offset:36864
	ds_read_b128 v[190:193], v202 offset:37888
	ds_read_b128 v[194:197], v202 offset:38912
	ds_read_b128 v[204:207], v202 offset:39936
	global_load_lds_dwordx4 v[214:215], off
	v_lshl_add_u64 v[214:215], s[42:43], 0, v[182:183]
	s_mov_b32 m0, s45
	s_nop 0
	global_load_lds_dwordx4 v[214:215], off
	s_waitcnt vmcnt(8)
	s_waitcnt lgkmcnt(0)
	s_barrier
	s_waitcnt lgkmcnt(0)
	v_mfma_f32_16x16x32_bf16 v[126:129], v[130:133], v[162:165], v[126:129]
	v_mfma_f32_16x16x32_bf16 v[126:129], v[134:137], v[166:169], v[126:129]
	v_mfma_f32_16x16x32_bf16 v[122:125], v[142:145], v[166:169], v[122:125]
	v_mfma_f32_16x16x32_bf16 v[122:125], v[138:141], v[162:165], v[122:125]
	v_mfma_f32_16x16x32_bf16 v[106:109], v[138:141], v[170:173], v[106:109]
	v_mfma_f32_16x16x32_bf16 v[106:109], v[142:145], v[174:177], v[106:109]
	v_mfma_f32_16x16x32_bf16 v[110:113], v[134:137], v[174:177], v[110:113]
	v_mfma_f32_16x16x32_bf16 v[110:113], v[130:133], v[170:173], v[110:113]
	v_mfma_f32_16x16x32_bf16 v[94:97], v[130:133], v[186:189], v[94:97]
	v_mfma_f32_16x16x32_bf16 v[94:97], v[134:137], v[190:193], v[94:97]
	v_mfma_f32_16x16x32_bf16 v[90:93], v[142:145], v[190:193], v[90:93]
	v_mfma_f32_16x16x32_bf16 v[90:93], v[138:141], v[186:189], v[90:93]
	v_mfma_f32_16x16x32_bf16 v[74:77], v[138:141], v[194:197], v[74:77]
	v_mfma_f32_16x16x32_bf16 v[74:77], v[142:145], v[204:207], v[74:77]
	v_mfma_f32_16x16x32_bf16 v[78:81], v[134:137], v[204:207], v[78:81]
	v_mfma_f32_16x16x32_bf16 v[78:81], v[130:133], v[194:197], v[78:81]
	v_mfma_f32_16x16x32_bf16 v[118:121], v[146:149], v[162:165], v[118:121]
	v_mfma_f32_16x16x32_bf16 v[118:121], v[150:153], v[166:169], v[118:121]
	v_mfma_f32_16x16x32_bf16 v[114:117], v[158:161], v[166:169], v[114:117]
	v_mfma_f32_16x16x32_bf16 v[114:117], v[154:157], v[162:165], v[114:117]
	v_mfma_f32_16x16x32_bf16 v[98:101], v[154:157], v[170:173], v[98:101]
	v_mfma_f32_16x16x32_bf16 v[98:101], v[158:161], v[174:177], v[98:101]
	v_mfma_f32_16x16x32_bf16 v[102:105], v[150:153], v[174:177], v[102:105]
	v_mfma_f32_16x16x32_bf16 v[102:105], v[146:149], v[170:173], v[102:105]
	v_mfma_f32_16x16x32_bf16 v[86:89], v[146:149], v[186:189], v[86:89]
	v_mfma_f32_16x16x32_bf16 v[86:89], v[150:153], v[190:193], v[86:89]
	v_mfma_f32_16x16x32_bf16 v[82:85], v[158:161], v[190:193], v[82:85]
	v_mfma_f32_16x16x32_bf16 v[82:85], v[154:157], v[186:189], v[82:85]
	v_mfma_f32_16x16x32_bf16 v[66:69], v[154:157], v[194:197], v[66:69]
	v_mfma_f32_16x16x32_bf16 v[66:69], v[158:161], v[204:207], v[66:69]
	v_mfma_f32_16x16x32_bf16 v[70:73], v[150:153], v[204:207], v[70:73]
	v_mfma_f32_16x16x32_bf16 v[70:73], v[146:149], v[194:197], v[70:73]
	s_barrier
	s_add_i32 s42, s57, s2
	v_lshl_add_u64 v[208:209], v[208:209], 0, s[16:17]
	s_mov_b32 m0, s42
	ds_read_b128 v[162:165], v202 offset:49152
	ds_read_b128 v[166:169], v202 offset:50176
	ds_read_b128 v[170:173], v202 offset:51200
	ds_read_b128 v[174:177], v202 offset:52224
	ds_read_b128 v[186:189], v202 offset:53248
	ds_read_b128 v[190:193], v202 offset:54272
	ds_read_b128 v[194:197], v202 offset:55296
	ds_read_b128 v[204:207], v202 offset:56320
	global_load_lds_dwordx4 v[208:209], off
	s_add_i32 m0, s42, 0x2000
	s_add_u32 s40, s40, 0x208080
	v_lshl_add_u64 v[208:209], v[210:211], 0, s[16:17]
	s_addc_u32 s41, s41, 0
	s_add_i32 s42, s58, s2
	global_load_lds_dwordx4 v[208:209], off
	v_lshl_add_u64 v[208:209], s[40:41], 0, v[180:181]
	s_mov_b32 m0, s42
	s_nop 0
	global_load_lds_dwordx4 v[208:209], off
	v_lshl_add_u64 v[208:209], s[40:41], 0, v[184:185]
	s_add_i32 m0, s42, 0x2000
	s_nop 0
	global_load_lds_dwordx4 v[208:209], off
	v_lshl_add_u64 v[208:209], s[36:37], 0, v[178:179]
	s_mov_b32 m0, s47
	s_nop 0
	global_load_lds_dwordx4 v[208:209], off
	v_lshl_add_u64 v[208:209], s[36:37], 0, v[182:183]
	s_mov_b32 m0, s48
	s_nop 0
	global_load_lds_dwordx4 v[208:209], off
	s_waitcnt vmcnt(8)
	s_waitcnt lgkmcnt(0)
	s_barrier
	s_waitcnt lgkmcnt(0)
	v_mfma_f32_16x16x32_bf16 v[62:65], v[130:133], v[162:165], v[62:65]
	v_mfma_f32_16x16x32_bf16 v[62:65], v[134:137], v[166:169], v[62:65]
	v_mfma_f32_16x16x32_bf16 v[58:61], v[142:145], v[166:169], v[58:61]
	v_mfma_f32_16x16x32_bf16 v[58:61], v[138:141], v[162:165], v[58:61]
	v_mfma_f32_16x16x32_bf16 v[42:45], v[138:141], v[170:173], v[42:45]
	v_mfma_f32_16x16x32_bf16 v[42:45], v[142:145], v[174:177], v[42:45]
	v_mfma_f32_16x16x32_bf16 v[46:49], v[134:137], v[174:177], v[46:49]
	v_mfma_f32_16x16x32_bf16 v[46:49], v[130:133], v[170:173], v[46:49]
	v_mfma_f32_16x16x32_bf16 v[30:33], v[130:133], v[186:189], v[30:33]
	v_mfma_f32_16x16x32_bf16 v[30:33], v[134:137], v[190:193], v[30:33]
	v_mfma_f32_16x16x32_bf16 v[26:29], v[142:145], v[190:193], v[26:29]
	v_mfma_f32_16x16x32_bf16 v[26:29], v[138:141], v[186:189], v[26:29]
	v_mfma_f32_16x16x32_bf16 v[10:13], v[138:141], v[194:197], v[10:13]
	v_mfma_f32_16x16x32_bf16 v[10:13], v[142:145], v[204:207], v[10:13]
	v_mfma_f32_16x16x32_bf16 v[14:17], v[134:137], v[204:207], v[14:17]
	v_mfma_f32_16x16x32_bf16 v[14:17], v[130:133], v[194:197], v[14:17]
	v_mfma_f32_16x16x32_bf16 v[54:57], v[146:149], v[162:165], v[54:57]
	v_mfma_f32_16x16x32_bf16 v[54:57], v[150:153], v[166:169], v[54:57]
	v_mfma_f32_16x16x32_bf16 v[50:53], v[158:161], v[166:169], v[50:53]
	v_mfma_f32_16x16x32_bf16 v[50:53], v[154:157], v[162:165], v[50:53]
	v_mfma_f32_16x16x32_bf16 v[34:37], v[154:157], v[170:173], v[34:37]
	v_mfma_f32_16x16x32_bf16 v[34:37], v[158:161], v[174:177], v[34:37]
	v_mfma_f32_16x16x32_bf16 v[38:41], v[150:153], v[174:177], v[38:41]
	v_mfma_f32_16x16x32_bf16 v[38:41], v[146:149], v[170:173], v[38:41]
	v_mfma_f32_16x16x32_bf16 v[22:25], v[146:149], v[186:189], v[22:25]
	v_mfma_f32_16x16x32_bf16 v[22:25], v[150:153], v[190:193], v[22:25]
	v_mfma_f32_16x16x32_bf16 v[18:21], v[158:161], v[190:193], v[18:21]
	v_mfma_f32_16x16x32_bf16 v[18:21], v[154:157], v[186:189], v[18:21]
	v_mfma_f32_16x16x32_bf16 v[2:5], v[154:157], v[194:197], v[2:5]
	v_mfma_f32_16x16x32_bf16 v[2:5], v[158:161], v[204:207], v[2:5]
	v_mfma_f32_16x16x32_bf16 v[6:9], v[150:153], v[204:207], v[6:9]
	v_mfma_f32_16x16x32_bf16 v[6:9], v[146:149], v[194:197], v[6:9]
	s_barrier
	s_add_i32 s55, s55, 2
	s_add_i32 s56, s56, 0x10000
	s_cmpk_gt_u32 s55, 0x7d
	s_mov_b64 s[36:37], s[38:39]
	s_cbranch_scc0 .LBB0_519
	s_and_b64 vcc, exec, s[18:19]
	s_cbranch_vccz .LBB0_522
	s_barrier

.LBB0_612:
	ds_read_b128 v[166:169], v152
	ds_read_b128 v[170:173], v152 offset:1024
	ds_read_b128 v[174:177], v152 offset:2048
	ds_read_b128 v[178:181], v152 offset:3072
	ds_read_b128 v[182:185], v153
	ds_read_b128 v[186:189], v153 offset:1024
	ds_read_b128 v[190:193], v153 offset:2048
	ds_read_b128 v[194:197], v153 offset:3072
	s_add_u32 s26, s4, s22
	s_addc_u32 s27, s5, s23
	s_add_u32 s30, s26, 0x100
	s_addc_u32 s31, s27, 0
	s_add_u32 s28, s52, s22
	s_addc_u32 s29, s53, s23
	s_add_u32 s26, s26, 0x180
	s_addc_u32 s27, s27, 0
	s_cmpk_eq_i32 s22, 0x1f00
	s_cselect_b32 s27, s51, s27
	s_cselect_b32 s26, s50, s26
	s_cselect_b32 s29, s21, s29
	s_cselect_b32 s28, s20, s28
	s_cselect_b32 s31, s19, s31
	s_cselect_b32 s30, s18, s30
	s_mov_b32 m0, s37
	v_lshl_add_u64 v[210:211], v[148:149], 0, s[22:23]
	ds_read_b128 v[198:201], v154
	ds_read_b128 v[202:205], v154 offset:1024
	ds_read_b128 v[206:209], v154 offset:2048
	ds_read_b128 v[214:217], v154 offset:3072
	ds_read_b128 v[218:221], v154 offset:4096
	ds_read_b128 v[222:225], v154 offset:5120
	ds_read_b128 v[226:229], v154 offset:6144
	ds_read_b128 v[230:233], v154 offset:7168
	global_load_lds_dwordx4 v[210:211], off
	v_lshl_add_u64 v[210:211], v[150:151], 0, s[22:23]
	s_mov_b32 m0, s38
	s_nop 0
	global_load_lds_dwordx4 v[210:211], off
	s_waitcnt vmcnt(8)
	s_waitcnt lgkmcnt(0)
	s_barrier
	s_waitcnt lgkmcnt(0)
	v_mfma_f32_16x16x32_bf16 v[126:129], v[166:169], v[198:201], v[126:129]
	v_mfma_f32_16x16x32_bf16 v[126:129], v[170:173], v[202:205], v[126:129]
	v_mfma_f32_16x16x32_bf16 v[122:125], v[178:181], v[202:205], v[122:125]
	v_mfma_f32_16x16x32_bf16 v[122:125], v[174:177], v[198:201], v[122:125]
	v_mfma_f32_16x16x32_bf16 v[106:109], v[174:177], v[206:209], v[106:109]
	v_mfma_f32_16x16x32_bf16 v[106:109], v[178:181], v[214:217], v[106:109]
	v_mfma_f32_16x16x32_bf16 v[110:113], v[170:173], v[214:217], v[110:113]
	v_mfma_f32_16x16x32_bf16 v[110:113], v[166:169], v[206:209], v[110:113]
	v_mfma_f32_16x16x32_bf16 v[94:97], v[166:169], v[218:221], v[94:97]
	v_mfma_f32_16x16x32_bf16 v[94:97], v[170:173], v[222:225], v[94:97]
	v_mfma_f32_16x16x32_bf16 v[90:93], v[178:181], v[222:225], v[90:93]
	v_mfma_f32_16x16x32_bf16 v[90:93], v[174:177], v[218:221], v[90:93]
	v_mfma_f32_16x16x32_bf16 v[74:77], v[174:177], v[226:229], v[74:77]
	v_mfma_f32_16x16x32_bf16 v[74:77], v[178:181], v[230:233], v[74:77]
	v_mfma_f32_16x16x32_bf16 v[78:81], v[170:173], v[230:233], v[78:81]
	v_mfma_f32_16x16x32_bf16 v[78:81], v[166:169], v[226:229], v[78:81]
	v_mfma_f32_16x16x32_bf16 v[118:121], v[182:185], v[198:201], v[118:121]
	v_mfma_f32_16x16x32_bf16 v[118:121], v[186:189], v[202:205], v[118:121]
	v_mfma_f32_16x16x32_bf16 v[114:117], v[194:197], v[202:205], v[114:117]
	v_mfma_f32_16x16x32_bf16 v[114:117], v[190:193], v[198:201], v[114:117]
	v_mfma_f32_16x16x32_bf16 v[98:101], v[190:193], v[206:209], v[98:101]
	v_mfma_f32_16x16x32_bf16 v[98:101], v[194:197], v[214:217], v[98:101]
	v_mfma_f32_16x16x32_bf16 v[102:105], v[186:189], v[214:217], v[102:105]
	v_mfma_f32_16x16x32_bf16 v[102:105], v[182:185], v[206:209], v[102:105]
	v_mfma_f32_16x16x32_bf16 v[86:89], v[182:185], v[218:221], v[86:89]
	v_mfma_f32_16x16x32_bf16 v[86:89], v[186:189], v[222:225], v[86:89]
	v_mfma_f32_16x16x32_bf16 v[82:85], v[194:197], v[222:225], v[82:85]
	v_mfma_f32_16x16x32_bf16 v[82:85], v[190:193], v[218:221], v[82:85]
	v_mfma_f32_16x16x32_bf16 v[66:69], v[190:193], v[226:229], v[66:69]
	v_mfma_f32_16x16x32_bf16 v[66:69], v[194:197], v[230:233], v[66:69]
	v_mfma_f32_16x16x32_bf16 v[70:73], v[186:189], v[230:233], v[70:73]
	v_mfma_f32_16x16x32_bf16 v[70:73], v[182:185], v[226:229], v[70:73]
	s_barrier
	s_mov_b32 m0, s39
	v_lshl_add_u64 v[210:211], s[28:29], 0, v[132:133]
	s_add_u32 s56, s28, 0x108000
	ds_read_b128 v[198:201], v154 offset:16384
	ds_read_b128 v[202:205], v154 offset:17408
	ds_read_b128 v[206:209], v154 offset:18432
	ds_read_b128 v[214:217], v154 offset:19456
	ds_read_b128 v[218:221], v154 offset:20480
	ds_read_b128 v[222:225], v154 offset:21504
	ds_read_b128 v[226:229], v154 offset:22528
	ds_read_b128 v[230:233], v154 offset:23552
	global_load_lds_dwordx4 v[210:211], off
	v_lshl_add_u64 v[234:235], s[28:29], 0, v[136:137]
	s_mov_b32 m0, s40
	s_addc_u32 s57, s29, 0
	global_load_lds_dwordx4 v[234:235], off
	v_lshl_add_u64 v[236:237], s[56:57], 0, v[132:133]
	s_mov_b32 m0, s41
	s_nop 0
	global_load_lds_dwordx4 v[236:237], off
	v_lshl_add_u64 v[236:237], s[56:57], 0, v[136:137]
	s_mov_b32 m0, s42
	s_nop 0
	global_load_lds_dwordx4 v[236:237], off
	v_lshl_add_u64 v[236:237], s[30:31], 0, v[130:131]
	s_mov_b32 m0, s2
	s_nop 0
	global_load_lds_dwordx4 v[236:237], off
	v_lshl_add_u64 v[236:237], s[30:31], 0, v[134:135]
	s_mov_b32 m0, s3
	s_nop 0
	global_load_lds_dwordx4 v[236:237], off
	s_waitcnt vmcnt(8)
	s_waitcnt lgkmcnt(0)
	s_barrier
	s_waitcnt lgkmcnt(0)
	v_mfma_f32_16x16x32_bf16 v[62:65], v[166:169], v[198:201], v[62:65]
	v_mfma_f32_16x16x32_bf16 v[62:65], v[170:173], v[202:205], v[62:65]
	v_mfma_f32_16x16x32_bf16 v[58:61], v[178:181], v[202:205], v[58:61]
	v_mfma_f32_16x16x32_bf16 v[58:61], v[174:177], v[198:201], v[58:61]
	v_mfma_f32_16x16x32_bf16 v[42:45], v[174:177], v[206:209], v[42:45]
	v_mfma_f32_16x16x32_bf16 v[42:45], v[178:181], v[214:217], v[42:45]
	v_mfma_f32_16x16x32_bf16 v[46:49], v[170:173], v[214:217], v[46:49]
	v_mfma_f32_16x16x32_bf16 v[46:49], v[166:169], v[206:209], v[46:49]
	v_mfma_f32_16x16x32_bf16 v[30:33], v[166:169], v[218:221], v[30:33]
	v_mfma_f32_16x16x32_bf16 v[30:33], v[170:173], v[222:225], v[30:33]
	v_mfma_f32_16x16x32_bf16 v[26:29], v[178:181], v[222:225], v[26:29]
	v_mfma_f32_16x16x32_bf16 v[26:29], v[174:177], v[218:221], v[26:29]
	v_mfma_f32_16x16x32_bf16 v[10:13], v[174:177], v[226:229], v[10:13]
	v_mfma_f32_16x16x32_bf16 v[10:13], v[178:181], v[230:233], v[10:13]
	v_mfma_f32_16x16x32_bf16 v[14:17], v[170:173], v[230:233], v[14:17]
	v_mfma_f32_16x16x32_bf16 v[14:17], v[166:169], v[226:229], v[14:17]
	v_mfma_f32_16x16x32_bf16 v[54:57], v[182:185], v[198:201], v[54:57]
	v_mfma_f32_16x16x32_bf16 v[54:57], v[186:189], v[202:205], v[54:57]
	v_mfma_f32_16x16x32_bf16 v[50:53], v[194:197], v[202:205], v[50:53]
	v_mfma_f32_16x16x32_bf16 v[50:53], v[190:193], v[198:201], v[50:53]
	v_mfma_f32_16x16x32_bf16 v[34:37], v[190:193], v[206:209], v[34:37]
	v_mfma_f32_16x16x32_bf16 v[34:37], v[194:197], v[214:217], v[34:37]
	v_mfma_f32_16x16x32_bf16 v[38:41], v[186:189], v[214:217], v[38:41]
	v_mfma_f32_16x16x32_bf16 v[38:41], v[182:185], v[206:209], v[38:41]
	v_mfma_f32_16x16x32_bf16 v[22:25], v[182:185], v[218:221], v[22:25]
	v_mfma_f32_16x16x32_bf16 v[22:25], v[186:189], v[222:225], v[22:25]
	v_mfma_f32_16x16x32_bf16 v[18:21], v[194:197], v[222:225], v[18:21]
	v_mfma_f32_16x16x32_bf16 v[18:21], v[190:193], v[218:221], v[18:21]
	v_mfma_f32_16x16x32_bf16 v[2:5], v[190:193], v[226:229], v[2:5]
	v_mfma_f32_16x16x32_bf16 v[2:5], v[194:197], v[230:233], v[2:5]
	v_mfma_f32_16x16x32_bf16 v[6:9], v[186:189], v[230:233], v[6:9]
	v_mfma_f32_16x16x32_bf16 v[6:9], v[182:185], v[226:229], v[6:9]
	s_barrier
	ds_read_b128 v[166:169], v156
	ds_read_b128 v[170:173], v156 offset:1024
	ds_read_b128 v[174:177], v156 offset:2048
	ds_read_b128 v[178:181], v156 offset:3072
	ds_read_b128 v[182:185], v157
	ds_read_b128 v[186:189], v157 offset:1024
	ds_read_b128 v[190:193], v157 offset:2048
	ds_read_b128 v[194:197], v157 offset:3072
	s_add_u32 s30, s30, 0x108000
	s_addc_u32 s31, s31, 0
	s_mov_b32 m0, s33
	v_lshl_add_u64 v[236:237], s[30:31], 0, v[130:131]
	ds_read_b128 v[198:201], v154 offset:32768
	ds_read_b128 v[202:205], v154 offset:33792
	ds_read_b128 v[206:209], v154 offset:34816
	ds_read_b128 v[214:217], v154 offset:35840
	ds_read_b128 v[218:221], v154 offset:36864
	ds_read_b128 v[222:225], v154 offset:37888
	ds_read_b128 v[226:229], v154 offset:38912
	ds_read_b128 v[230:233], v154 offset:39936
	global_load_lds_dwordx4 v[236:237], off
	v_lshl_add_u64 v[236:237], s[30:31], 0, v[134:135]
	s_mov_b32 m0, s34
	s_nop 0
	global_load_lds_dwordx4 v[236:237], off
	s_waitcnt vmcnt(8)
	s_waitcnt lgkmcnt(0)
	s_barrier
	s_waitcnt lgkmcnt(0)
	v_mfma_f32_16x16x32_bf16 v[126:129], v[166:169], v[198:201], v[126:129]
	v_mfma_f32_16x16x32_bf16 v[126:129], v[170:173], v[202:205], v[126:129]
	v_mfma_f32_16x16x32_bf16 v[122:125], v[178:181], v[202:205], v[122:125]
	v_mfma_f32_16x16x32_bf16 v[122:125], v[174:177], v[198:201], v[122:125]
	v_mfma_f32_16x16x32_bf16 v[106:109], v[174:177], v[206:209], v[106:109]
	v_mfma_f32_16x16x32_bf16 v[106:109], v[178:181], v[214:217], v[106:109]
	v_mfma_f32_16x16x32_bf16 v[110:113], v[170:173], v[214:217], v[110:113]
	v_mfma_f32_16x16x32_bf16 v[110:113], v[166:169], v[206:209], v[110:113]
	v_mfma_f32_16x16x32_bf16 v[94:97], v[166:169], v[218:221], v[94:97]
	v_mfma_f32_16x16x32_bf16 v[94:97], v[170:173], v[222:225], v[94:97]
	v_mfma_f32_16x16x32_bf16 v[90:93], v[178:181], v[222:225], v[90:93]
	v_mfma_f32_16x16x32_bf16 v[90:93], v[174:177], v[218:221], v[90:93]
	v_mfma_f32_16x16x32_bf16 v[74:77], v[174:177], v[226:229], v[74:77]
	v_mfma_f32_16x16x32_bf16 v[74:77], v[178:181], v[230:233], v[74:77]
	v_mfma_f32_16x16x32_bf16 v[78:81], v[170:173], v[230:233], v[78:81]
	v_mfma_f32_16x16x32_bf16 v[78:81], v[166:169], v[226:229], v[78:81]
	v_mfma_f32_16x16x32_bf16 v[118:121], v[182:185], v[198:201], v[118:121]
	v_mfma_f32_16x16x32_bf16 v[118:121], v[186:189], v[202:205], v[118:121]
	v_mfma_f32_16x16x32_bf16 v[114:117], v[194:197], v[202:205], v[114:117]
	v_mfma_f32_16x16x32_bf16 v[114:117], v[190:193], v[198:201], v[114:117]
	v_mfma_f32_16x16x32_bf16 v[98:101], v[190:193], v[206:209], v[98:101]
	v_mfma_f32_16x16x32_bf16 v[98:101], v[194:197], v[214:217], v[98:101]
	v_mfma_f32_16x16x32_bf16 v[102:105], v[186:189], v[214:217], v[102:105]
	v_mfma_f32_16x16x32_bf16 v[102:105], v[182:185], v[206:209], v[102:105]
	v_mfma_f32_16x16x32_bf16 v[86:89], v[182:185], v[218:221], v[86:89]
	v_mfma_f32_16x16x32_bf16 v[86:89], v[186:189], v[222:225], v[86:89]
	v_mfma_f32_16x16x32_bf16 v[82:85], v[194:197], v[222:225], v[82:85]
	v_mfma_f32_16x16x32_bf16 v[82:85], v[190:193], v[218:221], v[82:85]
	v_mfma_f32_16x16x32_bf16 v[66:69], v[190:193], v[226:229], v[66:69]
	v_mfma_f32_16x16x32_bf16 v[66:69], v[194:197], v[230:233], v[66:69]
	v_mfma_f32_16x16x32_bf16 v[70:73], v[186:189], v[230:233], v[70:73]
	v_mfma_f32_16x16x32_bf16 v[70:73], v[182:185], v[226:229], v[70:73]
	s_barrier
	s_mov_b32 m0, s43
	v_lshl_add_u64 v[210:211], v[210:211], 0, s[14:15]
	s_add_u32 s28, s28, 0x108080
	ds_read_b128 v[198:201], v154 offset:49152
	ds_read_b128 v[202:205], v154 offset:50176
	ds_read_b128 v[206:209], v154 offset:51200
	ds_read_b128 v[214:217], v154 offset:52224
	ds_read_b128 v[218:221], v154 offset:53248
	ds_read_b128 v[222:225], v154 offset:54272
	ds_read_b128 v[226:229], v154 offset:55296
	ds_read_b128 v[230:233], v154 offset:56320
	global_load_lds_dwordx4 v[210:211], off
	v_lshl_add_u64 v[210:211], v[234:235], 0, s[14:15]
	s_mov_b32 m0, s44
	s_addc_u32 s29, s29, 0
	global_load_lds_dwordx4 v[210:211], off
	v_lshl_add_u64 v[210:211], s[28:29], 0, v[132:133]
	s_mov_b32 m0, s45
	s_nop 0
	global_load_lds_dwordx4 v[210:211], off
	v_lshl_add_u64 v[210:211], s[28:29], 0, v[136:137]
	s_mov_b32 m0, s46
	s_nop 0
	global_load_lds_dwordx4 v[210:211], off
	v_lshl_add_u64 v[210:211], s[26:27], 0, v[130:131]
	s_mov_b32 m0, s35
	s_nop 0
	global_load_lds_dwordx4 v[210:211], off
	v_lshl_add_u64 v[210:211], s[26:27], 0, v[134:135]
	s_mov_b32 m0, s36
	s_nop 0
	global_load_lds_dwordx4 v[210:211], off
	s_waitcnt vmcnt(8)
	s_waitcnt lgkmcnt(0)
	s_barrier
	s_waitcnt lgkmcnt(0)
	v_mfma_f32_16x16x32_bf16 v[62:65], v[166:169], v[198:201], v[62:65]
	v_mfma_f32_16x16x32_bf16 v[62:65], v[170:173], v[202:205], v[62:65]
	v_mfma_f32_16x16x32_bf16 v[58:61], v[178:181], v[202:205], v[58:61]
	v_mfma_f32_16x16x32_bf16 v[58:61], v[174:177], v[198:201], v[58:61]
	v_mfma_f32_16x16x32_bf16 v[42:45], v[174:177], v[206:209], v[42:45]
	v_mfma_f32_16x16x32_bf16 v[42:45], v[178:181], v[214:217], v[42:45]
	v_mfma_f32_16x16x32_bf16 v[46:49], v[170:173], v[214:217], v[46:49]
	v_mfma_f32_16x16x32_bf16 v[46:49], v[166:169], v[206:209], v[46:49]
	v_mfma_f32_16x16x32_bf16 v[30:33], v[166:169], v[218:221], v[30:33]
	v_mfma_f32_16x16x32_bf16 v[30:33], v[170:173], v[222:225], v[30:33]
	v_mfma_f32_16x16x32_bf16 v[26:29], v[178:181], v[222:225], v[26:29]
	v_mfma_f32_16x16x32_bf16 v[26:29], v[174:177], v[218:221], v[26:29]
	v_mfma_f32_16x16x32_bf16 v[10:13], v[174:177], v[226:229], v[10:13]
	v_mfma_f32_16x16x32_bf16 v[10:13], v[178:181], v[230:233], v[10:13]
	v_mfma_f32_16x16x32_bf16 v[14:17], v[170:173], v[230:233], v[14:17]
	v_mfma_f32_16x16x32_bf16 v[14:17], v[166:169], v[226:229], v[14:17]
	v_mfma_f32_16x16x32_bf16 v[54:57], v[182:185], v[198:201], v[54:57]
	v_mfma_f32_16x16x32_bf16 v[54:57], v[186:189], v[202:205], v[54:57]
	v_mfma_f32_16x16x32_bf16 v[50:53], v[194:197], v[202:205], v[50:53]
	v_mfma_f32_16x16x32_bf16 v[50:53], v[190:193], v[198:201], v[50:53]
	v_mfma_f32_16x16x32_bf16 v[34:37], v[190:193], v[206:209], v[34:37]
	v_mfma_f32_16x16x32_bf16 v[34:37], v[194:197], v[214:217], v[34:37]
	v_mfma_f32_16x16x32_bf16 v[38:41], v[186:189], v[214:217], v[38:41]
	v_mfma_f32_16x16x32_bf16 v[38:41], v[182:185], v[206:209], v[38:41]
	v_mfma_f32_16x16x32_bf16 v[22:25], v[182:185], v[218:221], v[22:25]
	v_mfma_f32_16x16x32_bf16 v[22:25], v[186:189], v[222:225], v[22:25]
	v_mfma_f32_16x16x32_bf16 v[18:21], v[194:197], v[222:225], v[18:21]
	v_mfma_f32_16x16x32_bf16 v[18:21], v[190:193], v[218:221], v[18:21]
	v_mfma_f32_16x16x32_bf16 v[2:5], v[190:193], v[226:229], v[2:5]
	v_mfma_f32_16x16x32_bf16 v[2:5], v[194:197], v[230:233], v[2:5]
	v_mfma_f32_16x16x32_bf16 v[6:9], v[186:189], v[230:233], v[6:9]
	v_mfma_f32_16x16x32_bf16 v[6:9], v[182:185], v[226:229], v[6:9]
	s_barrier
	s_add_i32 s54, s54, 2
	s_add_u32 s22, s22, 0x100
	s_addc_u32 s23, s23, 0
	s_cmp_gt_u32 s54, 61
	s_cbranch_scc0 .LBB0_612
	s_and_b64 vcc, exec, s[16:17]
	s_cbranch_vccz .LBB0_615
	s_barrier

.LBB0_720:
	v_writelane_b32 v254, s80, 53
	s_cmp_lt_i32 s70, 8
	s_cselect_b64 s[0:1], -1, 0
	v_writelane_b32 v254, s81, 54
	v_writelane_b32 v254, s82, 55
	v_writelane_b32 v254, s83, 56
	s_and_b64 s[0:1], s[0:1], s[4:5]
	v_writelane_b32 v254, s0, 57
	s_andn2_b64 vcc, exec, s[0:1]
	s_nop 0
	v_writelane_b32 v254, s1, 58
	s_cbranch_vccnz .LBB0_772
	s_cmp_ge_u32 s87, 0x100
	s_cbranch_scc1 .Lp7_prio_skip
	s_setprio 1
.Lp7_prio_skip:
	v_writelane_b32 v254, s72, 59
	v_lshlrev_b32_e32 v1, 2, v212
	s_and_b32 s85, s87, 0xffffffc0
	v_writelane_b32 v254, s73, 60
	v_writelane_b32 v255, s86, 0
	v_readlane_b32 s0, v254, 2
	v_readlane_b32 s6, v254, 8
	v_readlane_b32 s7, v254, 9
	v_readlane_b32 s8, v254, 10
	v_readlane_b32 s9, v254, 11
	v_readlane_b32 s10, v254, 12
	v_readlane_b32 s11, v254, 13
	v_readlane_b32 s12, v254, 14
	v_readlane_b32 s13, v254, 15
	global_load_dword v2, v1, s[6:7]
	s_waitcnt lgkmcnt(0)
	global_load_dword v3, v1, s[8:9]
	global_load_dword v4, v1, s[6:7] offset:256
	global_load_dword v5, v1, s[8:9] offset:256
	global_load_dword v6, v1, s[10:11] offset:256
	global_load_dword v7, v1, s[12:13] offset:256
	global_load_dword v8, v1, s[10:11]
	global_load_dword v9, v1, s[12:13]
	v_mbcnt_lo_u32_b32 v1, -1, 0
	v_mbcnt_hi_u32_b32 v1, -1, v1
	v_and_b32_e32 v10, 64, v1
	v_xor_b32_e32 v11, 1, v1
	v_add_u32_e32 v10, 64, v10
	v_cmp_lt_i32_e32 vcc, v11, v10
	v_xor_b32_e32 v12, 2, v1
	v_xor_b32_e32 v13, 4, v1
	v_cndmask_b32_e32 v11, v1, v11, vcc
	v_lshlrev_b32_e32 v11, 2, v11
	v_cmp_lt_i32_e32 vcc, v12, v10
	v_xor_b32_e32 v14, 8, v1
	v_xor_b32_e32 v15, 16, v1
	v_xor_b32_e32 v16, 32, v1
	v_readlane_b32 s2, v254, 4
	v_readlane_b32 s2, v254, 26
	s_lshl_b32 s0, s2, 8
	v_readlane_b32 s1, v254, 3
	s_add_i32 s0, s0, 0
	s_lshl_b32 s1, s2, 10
	s_add_i32 s0, s0, 0x20000
	v_readlane_b32 s3, v254, 5
	v_readlane_b32 s4, v254, 6
	v_readlane_b32 s5, v254, 7
	v_readlane_b32 s14, v254, 16
	v_readlane_b32 s15, v254, 17
	s_add_i32 s1, s1, 0
	v_writelane_b32 v254, s0, 61
	s_lshl_b32 s0, s2, 14
	v_writelane_b32 v254, s1, 62
	s_add_i32 s70, s1, 0x10000
	s_add_i32 s0, s0, 0
	v_writelane_b32 v254, s0, 63
	s_cmpk_gt_i32 s86, 0x2ff
	s_waitcnt vmcnt(0)
	v_mul_f32_e32 v4, v4, v5
	v_fmac_f32_e32 v4, v2, v3
	v_mul_f32_e32 v5, v6, v7
	ds_bpermute_b32 v2, v11, v4
	v_fmac_f32_e32 v5, v8, v9
	ds_bpermute_b32 v3, v11, v5
	v_cndmask_b32_e32 v6, v1, v12, vcc
	v_lshlrev_b32_e32 v6, 2, v6
	s_waitcnt lgkmcnt(1)
	v_add_f32_e32 v2, v4, v2
	ds_bpermute_b32 v4, v6, v2
	s_waitcnt lgkmcnt(1)
	v_add_f32_e32 v3, v5, v3
	ds_bpermute_b32 v5, v6, v3
	v_cmp_lt_i32_e32 vcc, v13, v10
	s_waitcnt lgkmcnt(1)
	v_add_f32_e32 v2, v2, v4
	v_cndmask_b32_e32 v6, v1, v13, vcc
	v_lshlrev_b32_e32 v6, 2, v6
	s_waitcnt lgkmcnt(0)
	v_add_f32_e32 v3, v3, v5
	ds_bpermute_b32 v4, v6, v2
	ds_bpermute_b32 v5, v6, v3
	v_cmp_lt_i32_e32 vcc, v14, v10
	s_waitcnt lgkmcnt(1)
	v_add_f32_e32 v2, v2, v4
	v_cndmask_b32_e32 v6, v1, v14, vcc
	v_lshlrev_b32_e32 v6, 2, v6
	s_waitcnt lgkmcnt(0)
	v_add_f32_e32 v3, v3, v5
	ds_bpermute_b32 v4, v6, v2
	ds_bpermute_b32 v5, v6, v3
	v_cmp_lt_i32_e32 vcc, v15, v10
	s_waitcnt lgkmcnt(1)
	v_add_f32_e32 v2, v2, v4
	v_cndmask_b32_e32 v6, v1, v15, vcc
	v_lshlrev_b32_e32 v213, 2, v6
	s_waitcnt lgkmcnt(0)
	v_add_f32_e32 v3, v3, v5
	ds_bpermute_b32 v4, v213, v2
	ds_bpermute_b32 v5, v213, v3
	v_cmp_lt_i32_e32 vcc, v16, v10
	s_waitcnt lgkmcnt(1)
	v_add_f32_e32 v2, v2, v4
	v_cndmask_b32_e32 v1, v1, v16, vcc
	v_lshlrev_b32_e32 v1, 2, v1
	s_waitcnt lgkmcnt(0)
	v_add_f32_e32 v3, v3, v5
	ds_bpermute_b32 v4, v1, v2
	ds_bpermute_b32 v5, v1, v3
	s_cbranch_scc1 .LBB0_766
	s_lshr_b32 s0, s87, 8
	s_bfe_u32 s1, s87, 0x20006
	s_lshl_b32 s2, s0, 14
	s_lshl_b32 s3, s1, 5
	s_add_i32 s2, s2, 0
	s_lshl_b32 s1, s1, 1
	s_lshl_b32 s20, s0, 7
	v_writelane_b32 v255, s2, 1
	s_add_i32 s2, s1, s0
	s_xor_b32 s0, s0, 1
	s_add_i32 s1, s1, s0
	s_lshl_b32 s2, s2, 14
	s_lshl_b32 s0, s1, 14
	s_add_i32 s2, s2, 0
	s_add_i32 s0, s0, 0
	v_writelane_b32 v255, s2, 2
	s_cmpk_lt_u32 s87, 0x100
	v_writelane_b32 v255, s0, 3
	s_cselect_b64 s[36:37], -1, 0
	s_and_b32 s0, s20, 0x80
	v_writelane_b32 v255, s0, 4
	s_xor_b32 s0, s85, 0x100
	s_lshl_b32 s0, s0, 2
	s_waitcnt lgkmcnt(1)
	v_add_f32_e32 v1, v2, v4
	s_waitcnt lgkmcnt(0)
	v_add_f32_e32 v2, v3, v5
	s_add_i32 s0, s0, 0
	v_mul_f32_e32 v1, 0x3fb8aa3b, v1
	v_mul_f32_e32 v2, 0x3fb8aa3b, v2
	s_add_i32 s0, s0, 0x20000
	v_exp_f32_e32 v1, v1
	v_exp_f32_e32 v2, v2
	v_writelane_b32 v255, s0, 5
	v_writelane_b32 v255, s3, 6
	s_sub_i32 s0, s3, 64
	v_writelane_b32 v255, s0, 7
	s_add_i32 s0, 0, 0x8000
	v_writelane_b32 v255, s0, 8
	v_sub_f32_e32 v1, v1, v2
	v_readlane_b32 s0, v255, 0
	v_writelane_b32 v255, s90, 9
	v_add_f32_e32 v210, 0x3eb60549, v1
	v_mov_b32_e32 v211, v210
	v_writelane_b32 v255, s91, 10
	s_movk_i32 s2, 0xf0
	v_mov_b32_e32 v3, 0
	s_mov_b32 s97, 0x3e0293ee
	s_mov_b32 s80, 0x40c00000
	s_mov_b32 s81, 0x42000000
	s_mov_b32 s82, 0x40400000
	s_mov_b32 s83, 0x41000000
	s_mov_b32 s92, 0x41100000
	s_mov_b32 s93, 0x41200000
	s_mov_b32 s77, 0x41300000
	s_mov_b32 s84, 0x41800000
	s_mov_b32 s33, 0x41880000
	s_mov_b32 s73, 0x41900000
	s_mov_b32 s96, 0x41980000
	s_mov_b32 s86, 0x41c00000
	s_mov_b32 s78, 0x41c80000
	s_mov_b32 s79, 0x41d00000
	s_mov_b32 s87, 0x41d80000
	v_mov_b32_e32 v214, 0x3727c5ac
	v_mov_b32_e32 v215, 0xff800000
	s_mov_b32 s7, s0
	v_writelane_b32 v255, s20, 11
	s_branch .LBB0_724

.LBB0_772:
	s_setprio 0
	v_readlane_b32 s66, v254, 28
	v_readlane_b32 s67, v254, 29
	s_cmp_gt_i32 s67, 8
	v_readlane_b32 s0, v254, 57
	s_cselect_b64 s[4:5], -1, 0
	v_readlane_b32 s1, v254, 58
	v_readlane_b32 s58, v254, 51
	s_and_b64 s[0:1], s[0:1], s[4:5]
	v_readlane_b32 s60, v254, 53
	v_readlane_b32 s59, v254, 52
	s_andn2_b64 vcc, exec, s[0:1]
	v_readlane_b32 s61, v254, 54
	v_readlane_b32 s62, v254, 55
	v_readlane_b32 s63, v254, 56
	v_readlane_b32 s64, v254, 49
	v_readlane_b32 s59, v254, 30
	v_readlane_b32 s65, v254, 50
	s_cbranch_vccnz .LBB0_826
	s_waitcnt vmcnt(0)
	s_waitcnt vmcnt(0) lgkmcnt(0)
	s_barrier
	s_mov_b64 s[6:7], exec
	v_readlane_b32 s0, v254, 20
	v_readlane_b32 s1, v254, 21
	s_and_b64 s[0:1], s[6:7], s[0:1]
	s_mov_b64 exec, s[0:1]
	s_cbranch_execz .LBB0_825
	s_add_i32 s0, 0, 0x20820
	v_mov_b32_e32 v1, s0
	s_waitcnt vmcnt(0) expcnt(0) lgkmcnt(0)
	ds_read_b32 v4, v1
	s_add_i32 s0, 0, 0x20824
	v_mov_b32_e32 v1, s0
	ds_read_b32 v2, v1
	s_waitcnt lgkmcnt(1)
	v_cmp_ne_u32_e32 vcc, 0, v4
	s_cbranch_vccnz .LBB0_789
	s_add_u32 s8, s62, 0x4200
	s_addc_u32 s9, s63, 0
	s_add_u32 s10, s62, 0x4400
	s_addc_u32 s11, s63, 0
	s_add_u32 s12, s62, 0x4500
	s_addc_u32 s13, s63, 0
	s_add_u32 s14, s62, 0x4600
	s_addc_u32 s15, s63, 0
	s_add_u32 s16, s62, 0x4700
	s_addc_u32 s17, s63, 0
	s_add_u32 s18, s62, 0x4800
	s_addc_u32 s19, s63, 0
	s_add_u32 s20, s62, 0x4900
	s_addc_u32 s21, s63, 0
	s_add_u32 s22, s62, 0x4a00
	s_addc_u32 s23, s63, 0
	s_add_u32 s24, s62, 0x4b00
	s_addc_u32 s25, s63, 0
	s_add_u32 s26, s62, 0x4c00
	s_addc_u32 s27, s63, 0
	s_add_u32 s28, s62, 0x4d00
	s_addc_u32 s29, s63, 0
	s_add_u32 s30, s62, 0x4e00
	s_addc_u32 s31, s63, 0
	s_add_u32 s34, s62, 0x4f00
	v_readlane_b32 s2, v254, 0
	s_addc_u32 s35, s63, 0
	v_readlane_b32 s3, v254, 1
	s_add_u32 s36, s62, 0x5000
	s_load_dwordx2 s[0:1], s[2:3], 0x4
	s_addc_u32 s37, s63, 0
	s_add_u32 s38, s62, 0x5100
	s_addc_u32 s39, s63, 0
	s_add_u32 s40, s62, 0x5200
	s_addc_u32 s41, s63, 0
	s_waitcnt lgkmcnt(0)
	s_mul_i32 s0, s0, s88
	s_add_u32 s42, s62, 0x5300
	s_mul_i32 s0, s0, s1
	s_addc_u32 s43, s63, 0
	s_mov_b32 s1, 1
	v_mov_b32_e32 v18, 0
	s_branch .LBB0_777

.LBB0_844:
	s_add_i32 s35, s52, 0xfffe8000
	s_and_b32 s34, s30, 0x100
	s_and_b32 s35, s35, 0x3e0000
	s_or_b32 s34, s34, s35
	s_add_u32 s53, s28, s34
	s_addc_u32 s55, s29, 0
	s_add_u32 s34, s30, 0x100
	s_addc_u32 s35, s31, 0
	s_add_i32 s37, s52, 0xffff8000
	s_and_b32 s36, s34, 0x100
	s_and_b32 s37, s37, 0x7e0000
	s_or_b32 s36, s37, s36
	s_add_u32 s36, s28, s36
	s_addc_u32 s37, s29, 0
	s_add_u32 s54, s49, s30
	s_addc_u32 s31, s50, s31
	s_add_i32 s38, s30, 0x180
	s_and_b32 s38, s38, 0x180
	s_and_b32 s39, s52, 0x7e0000
	s_or_b32 s38, s39, s38
	s_add_u32 s56, s28, s38
	s_addc_u32 s57, s29, 0
	s_cmpk_eq_i32 s30, 0x3f00
	s_cselect_b32 s39, s1, s37
	s_cselect_b32 s38, s21, s36
	s_cselect_b32 s37, s23, s31
	s_cselect_b32 s36, s22, s54
	s_cselect_b32 s31, s48, s57
	s_cselect_b32 s30, s27, s56
	s_add_i32 s56, 0, 0x10000
	v_add_u32_e32 v124, s56, v211
	ds_read_b128 v[104:107], v124
	ds_read_b128 v[108:111], v124 offset:1024
	ds_read_b128 v[120:123], v124 offset:2048
	ds_read_b128 v[124:127], v124 offset:3072
	ds_read_b128 v[144:147], v214
	ds_read_b128 v[148:151], v214 offset:1024
	ds_read_b128 v[152:155], v214 offset:2048
	ds_read_b128 v[156:159], v214 offset:3072
	s_add_u32 s54, s53, 0x10080
	s_addc_u32 s55, s55, 0
	v_lshl_add_u64 v[200:201], s[54:55], 0, v[184:185]
	s_add_i32 m0, s3, 0xc000
	ds_read_b128 v[160:163], v215
	ds_read_b128 v[164:167], v215 offset:1024
	ds_read_b128 v[168:171], v215 offset:2048
	ds_read_b128 v[172:175], v215 offset:3072
	ds_read_b128 v[176:179], v215 offset:4096
	ds_read_b128 v[180:183], v215 offset:5120
	ds_read_b128 v[192:195], v215 offset:6144
	ds_read_b128 v[196:199], v215 offset:7168
	global_load_lds_dwordx4 v[200:201], off
	v_lshl_add_u64 v[200:201], s[54:55], 0, v[188:189]
	s_add_i32 m0, s3, 0xe000
	s_nop 0
	global_load_lds_dwordx4 v[200:201], off
	s_waitcnt vmcnt(8)
	s_waitcnt lgkmcnt(0)
	s_barrier
	s_waitcnt lgkmcnt(0)
	v_mfma_f32_16x16x32_bf16 v[140:143], v[104:107], v[160:163], v[140:143]
	v_mfma_f32_16x16x32_bf16 v[140:143], v[108:111], v[164:167], v[140:143]
	v_mfma_f32_16x16x32_bf16 v[136:139], v[124:127], v[164:167], v[136:139]
	v_mfma_f32_16x16x32_bf16 v[136:139], v[120:123], v[160:163], v[136:139]
	v_mfma_f32_16x16x32_bf16 v[112:115], v[120:123], v[168:171], v[112:115]
	v_mfma_f32_16x16x32_bf16 v[112:115], v[124:127], v[172:175], v[112:115]
	v_mfma_f32_16x16x32_bf16 v[116:119], v[108:111], v[172:175], v[116:119]
	v_mfma_f32_16x16x32_bf16 v[116:119], v[104:107], v[168:171], v[116:119]
	v_mfma_f32_16x16x32_bf16 v[92:95], v[104:107], v[176:179], v[92:95]
	v_mfma_f32_16x16x32_bf16 v[92:95], v[108:111], v[180:183], v[92:95]
	v_mfma_f32_16x16x32_bf16 v[88:91], v[124:127], v[180:183], v[88:91]
	v_mfma_f32_16x16x32_bf16 v[88:91], v[120:123], v[176:179], v[88:91]
	v_mfma_f32_16x16x32_bf16 v[72:75], v[120:123], v[192:195], v[72:75]
	v_mfma_f32_16x16x32_bf16 v[72:75], v[124:127], v[196:199], v[72:75]
	v_mfma_f32_16x16x32_bf16 v[76:79], v[108:111], v[196:199], v[76:79]
	v_mfma_f32_16x16x32_bf16 v[76:79], v[104:107], v[192:195], v[76:79]
	v_mfma_f32_16x16x32_bf16 v[132:135], v[144:147], v[160:163], v[132:135]
	v_mfma_f32_16x16x32_bf16 v[132:135], v[148:151], v[164:167], v[132:135]
	v_mfma_f32_16x16x32_bf16 v[128:131], v[156:159], v[164:167], v[128:131]
	v_mfma_f32_16x16x32_bf16 v[128:131], v[152:155], v[160:163], v[128:131]
	v_mfma_f32_16x16x32_bf16 v[96:99], v[152:155], v[168:171], v[96:99]
	v_mfma_f32_16x16x32_bf16 v[96:99], v[156:159], v[172:175], v[96:99]
	v_mfma_f32_16x16x32_bf16 v[100:103], v[148:151], v[172:175], v[100:103]
	v_mfma_f32_16x16x32_bf16 v[100:103], v[144:147], v[168:171], v[100:103]
	v_mfma_f32_16x16x32_bf16 v[84:87], v[144:147], v[176:179], v[84:87]
	v_mfma_f32_16x16x32_bf16 v[84:87], v[148:151], v[180:183], v[84:87]
	v_mfma_f32_16x16x32_bf16 v[80:83], v[156:159], v[180:183], v[80:83]
	v_mfma_f32_16x16x32_bf16 v[80:83], v[152:155], v[176:179], v[80:83]
	v_mfma_f32_16x16x32_bf16 v[64:67], v[152:155], v[192:195], v[64:67]
	v_mfma_f32_16x16x32_bf16 v[64:67], v[156:159], v[196:199], v[64:67]
	v_mfma_f32_16x16x32_bf16 v[68:71], v[148:151], v[196:199], v[68:71]
	v_mfma_f32_16x16x32_bf16 v[68:71], v[144:147], v[192:195], v[68:71]
	s_barrier
	s_add_i32 s53, s56, s2
	v_lshl_add_u64 v[200:201], s[36:37], 0, v[186:187]
	s_mov_b32 m0, s53
	ds_read_b128 v[160:163], v215 offset:16384
	ds_read_b128 v[164:167], v215 offset:17408
	ds_read_b128 v[168:171], v215 offset:18432
	ds_read_b128 v[172:175], v215 offset:19456
	ds_read_b128 v[176:179], v215 offset:20480
	ds_read_b128 v[180:183], v215 offset:21504
	ds_read_b128 v[192:195], v215 offset:22528
	ds_read_b128 v[196:199], v215 offset:23552
	global_load_lds_dwordx4 v[200:201], off
	s_add_i32 m0, s53, 0x2000
	s_add_u32 s54, s36, 0x208000
	v_lshl_add_u64 v[202:203], s[36:37], 0, v[190:191]
	s_addc_u32 s55, s37, 0
	s_add_i32 s53, s45, s2
	global_load_lds_dwordx4 v[202:203], off
	v_lshl_add_u64 v[204:205], s[54:55], 0, v[186:187]
	s_mov_b32 m0, s53
	s_nop 0
	global_load_lds_dwordx4 v[204:205], off
	v_lshl_add_u64 v[204:205], s[54:55], 0, v[190:191]
	s_add_i32 m0, s53, 0x2000
	s_nop 0
	global_load_lds_dwordx4 v[204:205], off
	v_lshl_add_u64 v[204:205], s[38:39], 0, v[184:185]
	s_mov_b32 m0, s3
	s_nop 0
	global_load_lds_dwordx4 v[204:205], off
	v_lshl_add_u64 v[204:205], s[38:39], 0, v[188:189]
	s_mov_b32 m0, s33
	s_nop 0
	global_load_lds_dwordx4 v[204:205], off
	s_waitcnt vmcnt(8)
	s_waitcnt lgkmcnt(0)
	s_barrier
	s_waitcnt lgkmcnt(0)
	v_mfma_f32_16x16x32_bf16 v[60:63], v[104:107], v[160:163], v[60:63]
	v_mfma_f32_16x16x32_bf16 v[60:63], v[108:111], v[164:167], v[60:63]
	v_mfma_f32_16x16x32_bf16 v[56:59], v[124:127], v[164:167], v[56:59]
	v_mfma_f32_16x16x32_bf16 v[56:59], v[120:123], v[160:163], v[56:59]
	v_mfma_f32_16x16x32_bf16 v[40:43], v[120:123], v[168:171], v[40:43]
	v_mfma_f32_16x16x32_bf16 v[40:43], v[124:127], v[172:175], v[40:43]
	v_mfma_f32_16x16x32_bf16 v[44:47], v[108:111], v[172:175], v[44:47]
	v_mfma_f32_16x16x32_bf16 v[44:47], v[104:107], v[168:171], v[44:47]
	v_mfma_f32_16x16x32_bf16 v[28:31], v[104:107], v[176:179], v[28:31]
	v_mfma_f32_16x16x32_bf16 v[28:31], v[108:111], v[180:183], v[28:31]
	v_mfma_f32_16x16x32_bf16 v[24:27], v[124:127], v[180:183], v[24:27]
	v_mfma_f32_16x16x32_bf16 v[24:27], v[120:123], v[176:179], v[24:27]
	v_mfma_f32_16x16x32_bf16 v[8:11], v[120:123], v[192:195], v[8:11]
	v_mfma_f32_16x16x32_bf16 v[8:11], v[124:127], v[196:199], v[8:11]
	v_mfma_f32_16x16x32_bf16 v[12:15], v[108:111], v[196:199], v[12:15]
	v_mfma_f32_16x16x32_bf16 v[12:15], v[104:107], v[192:195], v[12:15]
	v_mfma_f32_16x16x32_bf16 v[52:55], v[144:147], v[160:163], v[52:55]
	v_mfma_f32_16x16x32_bf16 v[52:55], v[148:151], v[164:167], v[52:55]
	v_mfma_f32_16x16x32_bf16 v[48:51], v[156:159], v[164:167], v[48:51]
	v_mfma_f32_16x16x32_bf16 v[48:51], v[152:155], v[160:163], v[48:51]
	v_mfma_f32_16x16x32_bf16 v[32:35], v[152:155], v[168:171], v[32:35]
	v_mfma_f32_16x16x32_bf16 v[32:35], v[156:159], v[172:175], v[32:35]
	v_mfma_f32_16x16x32_bf16 v[36:39], v[148:151], v[172:175], v[36:39]
	v_mfma_f32_16x16x32_bf16 v[36:39], v[144:147], v[168:171], v[36:39]
	v_mfma_f32_16x16x32_bf16 v[20:23], v[144:147], v[176:179], v[20:23]
	v_mfma_f32_16x16x32_bf16 v[20:23], v[148:151], v[180:183], v[20:23]
	v_mfma_f32_16x16x32_bf16 v[16:19], v[156:159], v[180:183], v[16:19]
	v_mfma_f32_16x16x32_bf16 v[16:19], v[152:155], v[176:179], v[16:19]
	v_mfma_f32_16x16x32_bf16 v[0:3], v[152:155], v[192:195], v[0:3]
	v_mfma_f32_16x16x32_bf16 v[0:3], v[156:159], v[196:199], v[0:3]
	v_mfma_f32_16x16x32_bf16 v[4:7], v[148:151], v[196:199], v[4:7]
	v_mfma_f32_16x16x32_bf16 v[4:7], v[144:147], v[192:195], v[4:7]
	s_barrier
	s_add_i32 s53, 0, 0x18000
	s_add_i32 s54, 0, 0x1c000
	v_add_u32_e32 v124, s53, v211
	v_add_u32_e32 v156, s54, v211
	ds_read_b128 v[104:107], v124
	ds_read_b128 v[108:111], v124 offset:1024
	ds_read_b128 v[120:123], v124 offset:2048
	ds_read_b128 v[124:127], v124 offset:3072
	ds_read_b128 v[144:147], v156
	ds_read_b128 v[148:151], v156 offset:1024
	ds_read_b128 v[152:155], v156 offset:2048
	ds_read_b128 v[156:159], v156 offset:3072
	s_add_u32 s38, s38, 0x10000
	s_addc_u32 s39, s39, 0
	s_mov_b32 m0, s40
	v_lshl_add_u64 v[204:205], s[38:39], 0, v[184:185]
	ds_read_b128 v[160:163], v215 offset:32768
	ds_read_b128 v[164:167], v215 offset:33792
	ds_read_b128 v[168:171], v215 offset:34816
	ds_read_b128 v[172:175], v215 offset:35840
	ds_read_b128 v[176:179], v215 offset:36864
	ds_read_b128 v[180:183], v215 offset:37888
	ds_read_b128 v[192:195], v215 offset:38912
	ds_read_b128 v[196:199], v215 offset:39936
	global_load_lds_dwordx4 v[204:205], off
	v_lshl_add_u64 v[204:205], s[38:39], 0, v[188:189]
	s_mov_b32 m0, s41
	s_nop 0
	global_load_lds_dwordx4 v[204:205], off
	s_waitcnt vmcnt(8)
	s_waitcnt lgkmcnt(0)
	s_barrier
	s_waitcnt lgkmcnt(0)
	v_mfma_f32_16x16x32_bf16 v[140:143], v[104:107], v[160:163], v[140:143]
	v_mfma_f32_16x16x32_bf16 v[140:143], v[108:111], v[164:167], v[140:143]
	v_mfma_f32_16x16x32_bf16 v[136:139], v[124:127], v[164:167], v[136:139]
	v_mfma_f32_16x16x32_bf16 v[136:139], v[120:123], v[160:163], v[136:139]
	v_mfma_f32_16x16x32_bf16 v[112:115], v[120:123], v[168:171], v[112:115]
	v_mfma_f32_16x16x32_bf16 v[112:115], v[124:127], v[172:175], v[112:115]
	v_mfma_f32_16x16x32_bf16 v[116:119], v[108:111], v[172:175], v[116:119]
	v_mfma_f32_16x16x32_bf16 v[116:119], v[104:107], v[168:171], v[116:119]
	v_mfma_f32_16x16x32_bf16 v[92:95], v[104:107], v[176:179], v[92:95]
	v_mfma_f32_16x16x32_bf16 v[92:95], v[108:111], v[180:183], v[92:95]
	v_mfma_f32_16x16x32_bf16 v[88:91], v[124:127], v[180:183], v[88:91]
	v_mfma_f32_16x16x32_bf16 v[88:91], v[120:123], v[176:179], v[88:91]
	v_mfma_f32_16x16x32_bf16 v[72:75], v[120:123], v[192:195], v[72:75]
	v_mfma_f32_16x16x32_bf16 v[72:75], v[124:127], v[196:199], v[72:75]
	v_mfma_f32_16x16x32_bf16 v[76:79], v[108:111], v[196:199], v[76:79]
	v_mfma_f32_16x16x32_bf16 v[76:79], v[104:107], v[192:195], v[76:79]
	v_mfma_f32_16x16x32_bf16 v[132:135], v[144:147], v[160:163], v[132:135]
	v_mfma_f32_16x16x32_bf16 v[132:135], v[148:151], v[164:167], v[132:135]
	v_mfma_f32_16x16x32_bf16 v[128:131], v[156:159], v[164:167], v[128:131]
	v_mfma_f32_16x16x32_bf16 v[128:131], v[152:155], v[160:163], v[128:131]
	v_mfma_f32_16x16x32_bf16 v[96:99], v[152:155], v[168:171], v[96:99]
	v_mfma_f32_16x16x32_bf16 v[96:99], v[156:159], v[172:175], v[96:99]
	v_mfma_f32_16x16x32_bf16 v[100:103], v[148:151], v[172:175], v[100:103]
	v_mfma_f32_16x16x32_bf16 v[100:103], v[144:147], v[168:171], v[100:103]
	v_mfma_f32_16x16x32_bf16 v[84:87], v[144:147], v[176:179], v[84:87]
	v_mfma_f32_16x16x32_bf16 v[84:87], v[148:151], v[180:183], v[84:87]
	v_mfma_f32_16x16x32_bf16 v[80:83], v[156:159], v[180:183], v[80:83]
	v_mfma_f32_16x16x32_bf16 v[80:83], v[152:155], v[176:179], v[80:83]
	v_mfma_f32_16x16x32_bf16 v[64:67], v[152:155], v[192:195], v[64:67]
	v_mfma_f32_16x16x32_bf16 v[64:67], v[156:159], v[196:199], v[64:67]
	v_mfma_f32_16x16x32_bf16 v[68:71], v[148:151], v[196:199], v[68:71]
	v_mfma_f32_16x16x32_bf16 v[68:71], v[144:147], v[192:195], v[68:71]
	s_barrier
	s_add_i32 s38, s53, s2
	v_lshl_add_u64 v[200:201], v[200:201], 0, s[16:17]
	s_mov_b32 m0, s38
	ds_read_b128 v[160:163], v215 offset:49152
	ds_read_b128 v[164:167], v215 offset:50176
	ds_read_b128 v[168:171], v215 offset:51200
	ds_read_b128 v[172:175], v215 offset:52224
	ds_read_b128 v[176:179], v215 offset:53248
	ds_read_b128 v[180:183], v215 offset:54272
	ds_read_b128 v[192:195], v215 offset:55296
	ds_read_b128 v[196:199], v215 offset:56320
	global_load_lds_dwordx4 v[200:201], off
	s_add_i32 m0, s38, 0x2000
	s_add_u32 s36, s36, 0x208080
	v_lshl_add_u64 v[200:201], v[202:203], 0, s[16:17]
	s_addc_u32 s37, s37, 0
	s_add_i32 s38, s54, s2
	global_load_lds_dwordx4 v[200:201], off
	v_lshl_add_u64 v[200:201], s[36:37], 0, v[186:187]
	s_mov_b32 m0, s38
	s_nop 0
	global_load_lds_dwordx4 v[200:201], off
	v_lshl_add_u64 v[200:201], s[36:37], 0, v[190:191]
	s_add_i32 m0, s38, 0x2000
	s_nop 0
	global_load_lds_dwordx4 v[200:201], off
	v_lshl_add_u64 v[200:201], s[30:31], 0, v[184:185]
	s_mov_b32 m0, s43
	s_nop 0
	global_load_lds_dwordx4 v[200:201], off
	v_lshl_add_u64 v[200:201], s[30:31], 0, v[188:189]
	s_mov_b32 m0, s44
	s_nop 0
	global_load_lds_dwordx4 v[200:201], off
	s_waitcnt vmcnt(8)
	s_waitcnt lgkmcnt(0)
	s_barrier
	s_waitcnt lgkmcnt(0)
	v_mfma_f32_16x16x32_bf16 v[60:63], v[104:107], v[160:163], v[60:63]
	v_mfma_f32_16x16x32_bf16 v[60:63], v[108:111], v[164:167], v[60:63]
	v_mfma_f32_16x16x32_bf16 v[56:59], v[124:127], v[164:167], v[56:59]
	v_mfma_f32_16x16x32_bf16 v[56:59], v[120:123], v[160:163], v[56:59]
	v_mfma_f32_16x16x32_bf16 v[40:43], v[120:123], v[168:171], v[40:43]
	v_mfma_f32_16x16x32_bf16 v[40:43], v[124:127], v[172:175], v[40:43]
	v_mfma_f32_16x16x32_bf16 v[44:47], v[108:111], v[172:175], v[44:47]
	v_mfma_f32_16x16x32_bf16 v[44:47], v[104:107], v[168:171], v[44:47]
	v_mfma_f32_16x16x32_bf16 v[28:31], v[104:107], v[176:179], v[28:31]
	v_mfma_f32_16x16x32_bf16 v[28:31], v[108:111], v[180:183], v[28:31]
	v_mfma_f32_16x16x32_bf16 v[24:27], v[124:127], v[180:183], v[24:27]
	v_mfma_f32_16x16x32_bf16 v[24:27], v[120:123], v[176:179], v[24:27]
	v_mfma_f32_16x16x32_bf16 v[8:11], v[120:123], v[192:195], v[8:11]
	v_mfma_f32_16x16x32_bf16 v[8:11], v[124:127], v[196:199], v[8:11]
	v_mfma_f32_16x16x32_bf16 v[12:15], v[108:111], v[196:199], v[12:15]
	v_mfma_f32_16x16x32_bf16 v[12:15], v[104:107], v[192:195], v[12:15]
	v_mfma_f32_16x16x32_bf16 v[52:55], v[144:147], v[160:163], v[52:55]
	v_mfma_f32_16x16x32_bf16 v[52:55], v[148:151], v[164:167], v[52:55]
	v_mfma_f32_16x16x32_bf16 v[48:51], v[156:159], v[164:167], v[48:51]
	v_mfma_f32_16x16x32_bf16 v[48:51], v[152:155], v[160:163], v[48:51]
	v_mfma_f32_16x16x32_bf16 v[32:35], v[152:155], v[168:171], v[32:35]
	v_mfma_f32_16x16x32_bf16 v[32:35], v[156:159], v[172:175], v[32:35]
	v_mfma_f32_16x16x32_bf16 v[36:39], v[148:151], v[172:175], v[36:39]
	v_mfma_f32_16x16x32_bf16 v[36:39], v[144:147], v[168:171], v[36:39]
	v_mfma_f32_16x16x32_bf16 v[20:23], v[144:147], v[176:179], v[20:23]
	v_mfma_f32_16x16x32_bf16 v[20:23], v[148:151], v[180:183], v[20:23]
	v_mfma_f32_16x16x32_bf16 v[16:19], v[156:159], v[180:183], v[16:19]
	v_mfma_f32_16x16x32_bf16 v[16:19], v[152:155], v[176:179], v[16:19]
	v_mfma_f32_16x16x32_bf16 v[0:3], v[152:155], v[192:195], v[0:3]
	v_mfma_f32_16x16x32_bf16 v[0:3], v[156:159], v[196:199], v[0:3]
	v_mfma_f32_16x16x32_bf16 v[4:7], v[148:151], v[196:199], v[4:7]
	v_mfma_f32_16x16x32_bf16 v[4:7], v[144:147], v[192:195], v[4:7]
	s_barrier
	s_add_i32 s51, s51, 2
	s_add_i32 s52, s52, 0x10000
	s_cmpk_gt_u32 s51, 0x7d
	s_mov_b64 s[30:31], s[34:35]
	s_cbranch_scc0 .LBB0_844
	s_and_b64 vcc, exec, s[18:19]
	s_cbranch_vccz .LBB0_847
	s_barrier
